# drop L2 write-back (buffer_wbl2) in the 7 seams after phases whose stores are all write-through; ssq stores made sc1
# baseline (speedup 1.0000x reference)
.LBB0_446:
	s_andn2_saveexec_b64 s[0:1], s[8:9]
	s_cbranch_execz .LBB0_465
	s_mov_b64 s[0:1], exec
	s_waitcnt lgkmcnt(0)
	s_waitcnt vmcnt(0)
	v_mbcnt_lo_u32_b32 v1, s0, 0
	s_add_u32 s8, s70, 0x3400
	v_mbcnt_hi_u32_b32 v1, s1, v1
	s_addc_u32 s9, s71, 0
	v_cmp_eq_u32_e32 vcc, 0, v1
	s_and_saveexec_b64 s[10:11], vcc
	s_cbranch_execz .LBB0_449
	s_bcnt1_i32_b64 s0, s[0:1]
	v_mov_b32_e32 v2, 0
	v_mov_b32_e32 v3, s0
	global_atomic_add v2, v2, v3, s[8:9] sc0

.LBB0_887:
	v_lshl_add_u32 v182, s26, 8, v169
	v_lshl_or_b32 v180, s51, 8, v192
	v_ashrrev_i32_e32 v183, 31, v182
	v_ashrrev_i32_e32 v181, 31, v180
	v_lshl_add_u64 v[184:185], v[180:181], 2, s[4:5]
	v_lshlrev_b64 v[128:129], 12, v[182:183]
	v_lshl_add_u64 v[128:129], v[184:185], 0, v[128:129]
	global_load_dwordx4 v[198:201], v[128:129], off offset:528
	global_load_dwordx4 v[202:205], v[128:129], off offset:512
	v_lshlrev_b64 v[128:129], 10, v[182:183]
	v_lshl_add_u64 v[188:189], v[128:129], 0, v[180:181]
	v_lshl_add_u64 v[128:129], v[188:189], 2, s[4:5]
	global_load_dwordx4 v[206:209], v[128:129], off
	global_load_dwordx4 v[210:213], v[128:129], off offset:16
	v_or_b32_e32 v190, 16, v182
	v_or_b32_e32 v186, 32, v182
	v_ashrrev_i32_e32 v191, 31, v190
	v_ashrrev_i32_e32 v187, 31, v186
	v_lshlrev_b64 v[128:129], 12, v[190:191]
	v_lshlrev_b64 v[130:131], 12, v[186:187]
	v_lshl_add_u64 v[128:129], v[184:185], 0, v[128:129]
	v_lshl_add_u64 v[132:133], v[184:185], 0, v[130:131]
	global_load_dwordx4 v[152:155], v[128:129], off offset:16
	global_load_dwordx4 v[156:159], v[128:129], off
	global_load_dwordx4 v[144:147], v[128:129], off offset:528
	global_load_dwordx4 v[148:151], v[128:129], off offset:512
	global_load_dwordx4 v[136:139], v[132:133], off offset:16
	global_load_dwordx4 v[140:143], v[132:133], off
	s_nop 0
	global_load_dwordx4 v[128:131], v[132:133], off offset:528
	s_nop 0
	global_load_dwordx4 v[132:135], v[132:133], off offset:512
	v_and_b32_e32 v214, 64, v196
	v_xor_b32_e32 v197, 16, v196
	v_add_u32_e32 v214, 64, v214
	v_cmp_lt_i32_e32 vcc, v197, v214
	v_xor_b32_e32 v215, 32, v196
	v_lshl_add_u64 v[188:189], v[188:189], 1, s[12:13]
	v_cndmask_b32_e32 v197, v196, v197, vcc
	v_lshlrev_b32_e32 v197, 2, v197
	v_cmp_lt_i32_e32 vcc, v215, v214
	s_waitcnt vmcnt(8)
	v_pk_add_f32 v[200:201], v[114:115], v[200:201]
	v_pk_add_f32 v[204:205], v[118:119], v[204:205]
	v_pk_add_f32 v[202:203], v[116:117], v[202:203]
	v_pk_add_f32 v[112:113], v[112:113], v[198:199]
	v_pk_add_f32 v[126:127], v[126:127], v[208:209]
	v_pk_add_f32 v[124:125], v[124:125], v[206:207]
	v_pk_add_f32 v[122:123], v[122:123], v[212:213]
	v_pk_add_f32 v[120:121], v[120:121], v[210:211]
	v_mul_f32_e32 v119, v203, v203
	v_mul_f32_e32 v198, v205, v205
	v_mul_f32_e32 v199, v113, v113
	v_mul_f32_e32 v206, v201, v201
	v_cvt_pk_bf16_f32 v114, v202, v203
	v_cvt_pk_bf16_f32 v115, v204, v205
	v_cvt_pk_bf16_f32 v116, v112, v113
	v_cvt_pk_bf16_f32 v117, v200, v201
	v_mul_f32_e32 v113, v125, v125
	v_mul_f32_e32 v201, v127, v127
	v_mul_f32_e32 v203, v121, v121
	v_mul_f32_e32 v205, v123, v123
	v_fmac_f32_e32 v119, v202, v202
	v_fmac_f32_e32 v198, v204, v204
	v_fmac_f32_e32 v199, v112, v112
	v_fmac_f32_e32 v206, v200, v200
	v_fmac_f32_e32 v113, v124, v124
	v_fmac_f32_e32 v201, v126, v126
	v_fmac_f32_e32 v203, v120, v120
	v_fmac_f32_e32 v205, v122, v122
	v_cvt_pk_bf16_f32 v118, v124, v125
	v_add_f32_e32 v112, v119, v198
	v_add_f32_e32 v119, v199, v206
	v_add_f32_e32 v113, v113, v201
	v_add_f32_e32 v124, v203, v205
	v_add_f32_e32 v112, v112, v119
	v_add_f32_e32 v113, v113, v124
	v_add_f32_e32 v112, v113, v112
	ds_bpermute_b32 v113, v197, v112
	v_cndmask_b32_e32 v216, v196, v215, vcc
	v_lshlrev_b32_e32 v198, 2, v216
	v_cvt_pk_bf16_f32 v119, v126, v127
	v_cvt_pk_bf16_f32 v120, v120, v121
	s_waitcnt lgkmcnt(0)
	v_add_f32_e32 v112, v112, v113
	ds_bpermute_b32 v113, v198, v112
	v_cvt_pk_bf16_f32 v121, v122, v123
	global_store_dwordx4 v[188:189], v[118:121], off sc1
	s_nop 1
	v_lshl_add_u64 v[214:215], v[188:189], 0, s[14:15]
	global_store_dwordx4 v[214:215], v[114:117], off sc1
	s_nop 1
	s_and_saveexec_b64 s[0:1], s[6:7]
	s_cbranch_execz .LBB0_889
	s_waitcnt lgkmcnt(0)
	v_add_f32_e32 v114, v112, v113
	s_lshl_b32 s26, s51, 2
	v_lshlrev_b64 v[112:113], 6, v[182:183]
	s_ashr_i32 s27, s26, 31
	v_lshl_add_u64 v[112:113], s[18:19], 0, v[112:113]
	v_lshl_add_u64 v[112:113], s[26:27], 2, v[112:113]
	s_lshl_b32 s10, s45, 2
	v_lshl_add_u64 v[112:113], v[112:113], 0, s[10:11]
	global_store_dword v[112:113], v114, off sc1
.LBB0_889:
	s_or_b64 exec, exec, s[0:1]
	v_or_b32_e32 v188, 48, v182
	v_ashrrev_i32_e32 v189, 31, v188
	s_waitcnt lgkmcnt(0)
	v_lshlrev_b64 v[112:113], 12, v[188:189]
	v_lshl_add_u64 v[116:117], v[184:185], 0, v[112:113]
	global_load_dwordx4 v[120:123], v[116:117], off offset:16
	global_load_dwordx4 v[124:127], v[116:117], off
	global_load_dwordx4 v[112:115], v[116:117], off offset:528
	s_nop 0
	global_load_dwordx4 v[116:119], v[116:117], off offset:512
	s_waitcnt vmcnt(11)
	v_pk_add_f32 v[110:111], v[110:111], v[158:159]
	v_pk_add_f32 v[108:109], v[108:109], v[156:157]
	v_pk_add_f32 v[154:155], v[106:107], v[154:155]
	v_pk_add_f32 v[106:107], v[104:105], v[152:153]
	v_mul_f32_e32 v104, v109, v109
	v_mul_f32_e32 v105, v111, v111
	v_fmac_f32_e32 v104, v108, v108
	v_fmac_f32_e32 v105, v110, v110
	v_add_f32_e32 v104, v104, v105
	v_mul_f32_e32 v105, v107, v107
	v_mul_f32_e32 v152, v155, v155
	v_fmac_f32_e32 v105, v106, v106
	v_fmac_f32_e32 v152, v154, v154
	v_lshlrev_b64 v[200:201], 10, v[190:191]
	v_add_f32_e32 v105, v105, v152
	v_lshl_add_u64 v[200:201], v[200:201], 0, v[180:181]
	v_add_f32_e32 v152, v104, v105
	v_cvt_pk_bf16_f32 v104, v108, v109
	v_cvt_pk_bf16_f32 v105, v110, v111
	v_pk_add_f32 v[102:103], v[102:103], v[150:151]
	v_pk_add_f32 v[100:101], v[100:101], v[148:149]
	v_cvt_pk_bf16_f32 v106, v106, v107
	v_cvt_pk_bf16_f32 v107, v154, v155
	v_lshl_add_u64 v[108:109], v[200:201], 1, s[12:13]
	global_store_dwordx4 v[108:109], v[104:107], off sc1
	s_nop 1
	v_pk_add_f32 v[104:105], v[98:99], v[146:147]
	v_mul_f32_e32 v98, v101, v101
	v_mul_f32_e32 v99, v103, v103
	v_pk_add_f32 v[96:97], v[96:97], v[144:145]
	v_fmac_f32_e32 v98, v100, v100
	v_fmac_f32_e32 v99, v102, v102
	v_add_f32_e32 v98, v98, v99
	v_mul_f32_e32 v99, v97, v97
	v_mul_f32_e32 v106, v105, v105
	v_fmac_f32_e32 v99, v96, v96
	v_fmac_f32_e32 v106, v104, v104
	v_add_f32_e32 v99, v99, v106
	v_add_f32_e32 v98, v98, v99
	v_add_f32_e32 v106, v152, v98
	ds_bpermute_b32 v107, v197, v106
	v_cvt_pk_bf16_f32 v98, v100, v101
	v_cvt_pk_bf16_f32 v100, v96, v97
	v_cvt_pk_bf16_f32 v99, v102, v103
	v_cvt_pk_bf16_f32 v101, v104, v105
	s_waitcnt lgkmcnt(0)
	v_add_f32_e32 v96, v106, v107
	ds_bpermute_b32 v97, v198, v96
	v_lshl_add_u64 v[102:103], v[108:109], 0, s[14:15]
	global_store_dwordx4 v[102:103], v[98:101], off sc1
	s_nop 1
	s_and_saveexec_b64 s[0:1], s[6:7]
	s_cbranch_execz .LBB0_891
	s_waitcnt lgkmcnt(0)
	v_add_f32_e32 v98, v96, v97
	s_lshl_b32 s26, s51, 2
	v_lshlrev_b64 v[96:97], 6, v[190:191]
	s_ashr_i32 s27, s26, 31
	v_lshl_add_u64 v[96:97], s[18:19], 0, v[96:97]
	v_lshl_add_u64 v[96:97], s[26:27], 2, v[96:97]
	s_lshl_b32 s10, s45, 2
	v_lshl_add_u64 v[96:97], v[96:97], 0, s[10:11]
	global_store_dword v[96:97], v98, off sc1
.LBB0_891:
	s_or_b64 exec, exec, s[0:1]
	v_add_u32_e32 v144, 0x80, v182
	v_ashrrev_i32_e32 v145, 31, v144
	s_waitcnt lgkmcnt(0)
	v_lshlrev_b64 v[96:97], 12, v[144:145]
	v_lshl_add_u64 v[100:101], v[184:185], 0, v[96:97]
	global_load_dwordx4 v[104:107], v[100:101], off offset:16
	global_load_dwordx4 v[108:111], v[100:101], off
	global_load_dwordx4 v[96:99], v[100:101], off offset:528
	s_nop 0
	global_load_dwordx4 v[100:103], v[100:101], off offset:512
	s_waitcnt vmcnt(14)
	v_pk_add_f32 v[94:95], v[94:95], v[142:143]
	v_pk_add_f32 v[92:93], v[92:93], v[140:141]
	v_pk_add_f32 v[138:139], v[90:91], v[138:139]
	v_pk_add_f32 v[90:91], v[88:89], v[136:137]
	v_mul_f32_e32 v88, v93, v93
	v_mul_f32_e32 v89, v95, v95
	v_fmac_f32_e32 v88, v92, v92
	v_fmac_f32_e32 v89, v94, v94
	v_add_f32_e32 v88, v88, v89
	v_mul_f32_e32 v89, v91, v91
	v_mul_f32_e32 v136, v139, v139
	v_fmac_f32_e32 v89, v90, v90
	v_fmac_f32_e32 v136, v138, v138
	v_lshlrev_b64 v[146:147], 10, v[186:187]
	v_add_f32_e32 v89, v89, v136
	v_lshl_add_u64 v[146:147], v[146:147], 0, v[180:181]
	v_add_f32_e32 v136, v88, v89
	v_cvt_pk_bf16_f32 v88, v92, v93
	v_cvt_pk_bf16_f32 v89, v94, v95
	v_pk_add_f32 v[86:87], v[86:87], v[134:135]
	v_pk_add_f32 v[84:85], v[84:85], v[132:133]
	v_cvt_pk_bf16_f32 v90, v90, v91
	v_cvt_pk_bf16_f32 v91, v138, v139
	v_lshl_add_u64 v[92:93], v[146:147], 1, s[12:13]
	global_store_dwordx4 v[92:93], v[88:91], off sc1
	s_nop 1
	v_pk_add_f32 v[88:89], v[82:83], v[130:131]
	v_mul_f32_e32 v82, v85, v85
	v_mul_f32_e32 v83, v87, v87
	v_pk_add_f32 v[80:81], v[80:81], v[128:129]
	v_fmac_f32_e32 v82, v84, v84
	v_fmac_f32_e32 v83, v86, v86
	v_add_f32_e32 v82, v82, v83
	v_mul_f32_e32 v83, v81, v81
	v_mul_f32_e32 v90, v89, v89
	v_fmac_f32_e32 v83, v80, v80
	v_fmac_f32_e32 v90, v88, v88
	v_add_f32_e32 v83, v83, v90
	v_add_f32_e32 v82, v82, v83
	v_add_f32_e32 v90, v136, v82
	ds_bpermute_b32 v91, v197, v90
	v_cvt_pk_bf16_f32 v82, v84, v85
	v_cvt_pk_bf16_f32 v84, v80, v81
	v_cvt_pk_bf16_f32 v83, v86, v87
	v_cvt_pk_bf16_f32 v85, v88, v89
	s_waitcnt lgkmcnt(0)
	v_add_f32_e32 v80, v90, v91
	ds_bpermute_b32 v81, v198, v80
	v_lshl_add_u64 v[86:87], v[92:93], 0, s[14:15]
	global_store_dwordx4 v[86:87], v[82:85], off sc1
	s_nop 1
	s_and_saveexec_b64 s[0:1], s[6:7]
	s_cbranch_execz .LBB0_893
	s_waitcnt lgkmcnt(0)
	v_add_f32_e32 v82, v80, v81
	s_lshl_b32 s26, s51, 2
	v_lshlrev_b64 v[80:81], 6, v[186:187]
	s_ashr_i32 s27, s26, 31
	v_lshl_add_u64 v[80:81], s[18:19], 0, v[80:81]
	v_lshl_add_u64 v[80:81], s[26:27], 2, v[80:81]
	s_lshl_b32 s10, s45, 2
	v_lshl_add_u64 v[80:81], v[80:81], 0, s[10:11]
	global_store_dword v[80:81], v82, off sc1
.LBB0_893:
	s_or_b64 exec, exec, s[0:1]
	v_add_u32_e32 v128, 0x90, v182
	v_ashrrev_i32_e32 v129, 31, v128
	s_waitcnt lgkmcnt(0)
	v_lshlrev_b64 v[80:81], 12, v[128:129]
	v_lshl_add_u64 v[84:85], v[184:185], 0, v[80:81]
	global_load_dwordx4 v[88:91], v[84:85], off offset:16
	global_load_dwordx4 v[92:95], v[84:85], off
	global_load_dwordx4 v[80:83], v[84:85], off offset:528
	s_nop 0
	global_load_dwordx4 v[84:87], v[84:85], off offset:512
	s_waitcnt vmcnt(14)
	v_pk_add_f32 v[78:79], v[78:79], v[126:127]
	v_pk_add_f32 v[76:77], v[76:77], v[124:125]
	v_pk_add_f32 v[122:123], v[74:75], v[122:123]
	v_pk_add_f32 v[74:75], v[72:73], v[120:121]
	v_mul_f32_e32 v72, v77, v77
	v_mul_f32_e32 v73, v79, v79
	v_fmac_f32_e32 v72, v76, v76
	v_fmac_f32_e32 v73, v78, v78
	v_add_f32_e32 v72, v72, v73
	v_mul_f32_e32 v73, v75, v75
	v_mul_f32_e32 v120, v123, v123
	v_fmac_f32_e32 v73, v74, v74
	v_fmac_f32_e32 v120, v122, v122
	v_lshlrev_b64 v[130:131], 10, v[188:189]
	v_add_f32_e32 v73, v73, v120
	v_lshl_add_u64 v[130:131], v[130:131], 0, v[180:181]
	v_add_f32_e32 v120, v72, v73
	v_cvt_pk_bf16_f32 v72, v76, v77
	v_cvt_pk_bf16_f32 v73, v78, v79
	s_waitcnt vmcnt(14)
	v_pk_add_f32 v[70:71], v[70:71], v[118:119]
	v_pk_add_f32 v[68:69], v[68:69], v[116:117]
	v_cvt_pk_bf16_f32 v74, v74, v75
	v_cvt_pk_bf16_f32 v75, v122, v123
	v_lshl_add_u64 v[76:77], v[130:131], 1, s[12:13]
	global_store_dwordx4 v[76:77], v[72:75], off sc1
	s_nop 1
	v_pk_add_f32 v[72:73], v[66:67], v[114:115]
	v_mul_f32_e32 v66, v69, v69
	v_mul_f32_e32 v67, v71, v71
	v_pk_add_f32 v[64:65], v[64:65], v[112:113]
	v_fmac_f32_e32 v66, v68, v68
	v_fmac_f32_e32 v67, v70, v70
	v_add_f32_e32 v66, v66, v67
	v_mul_f32_e32 v67, v65, v65
	v_mul_f32_e32 v74, v73, v73
	v_fmac_f32_e32 v67, v64, v64
	v_fmac_f32_e32 v74, v72, v72
	v_add_f32_e32 v67, v67, v74
	v_add_f32_e32 v66, v66, v67
	v_add_f32_e32 v74, v120, v66
	ds_bpermute_b32 v75, v197, v74
	v_cvt_pk_bf16_f32 v66, v68, v69
	v_cvt_pk_bf16_f32 v68, v64, v65
	v_cvt_pk_bf16_f32 v67, v70, v71
	v_cvt_pk_bf16_f32 v69, v72, v73
	s_waitcnt lgkmcnt(0)
	v_add_f32_e32 v64, v74, v75
	ds_bpermute_b32 v65, v198, v64
	v_lshl_add_u64 v[70:71], v[76:77], 0, s[14:15]
	global_store_dwordx4 v[70:71], v[66:69], off sc1
	s_nop 1
	s_and_saveexec_b64 s[0:1], s[6:7]
	s_cbranch_execz .LBB0_895
	s_waitcnt lgkmcnt(0)
	v_add_f32_e32 v66, v64, v65
	s_lshl_b32 s26, s51, 2
	v_lshlrev_b64 v[64:65], 6, v[188:189]
	s_ashr_i32 s27, s26, 31
	v_lshl_add_u64 v[64:65], s[18:19], 0, v[64:65]
	v_lshl_add_u64 v[64:65], s[26:27], 2, v[64:65]
	s_lshl_b32 s10, s45, 2
	v_lshl_add_u64 v[64:65], v[64:65], 0, s[10:11]
	global_store_dword v[64:65], v66, off sc1
.LBB0_895:
	s_or_b64 exec, exec, s[0:1]
	v_add_u32_e32 v112, 0xa0, v182
	v_ashrrev_i32_e32 v113, 31, v112
	s_waitcnt lgkmcnt(0)
	v_lshlrev_b64 v[64:65], 12, v[112:113]
	v_lshl_add_u64 v[68:69], v[184:185], 0, v[64:65]
	global_load_dwordx4 v[72:75], v[68:69], off offset:16
	global_load_dwordx4 v[76:79], v[68:69], off
	global_load_dwordx4 v[64:67], v[68:69], off offset:528
	s_nop 0
	global_load_dwordx4 v[68:71], v[68:69], off offset:512
	s_waitcnt vmcnt(14)
	v_pk_add_f32 v[62:63], v[62:63], v[110:111]
	v_pk_add_f32 v[60:61], v[60:61], v[108:109]
	v_pk_add_f32 v[106:107], v[58:59], v[106:107]
	v_pk_add_f32 v[58:59], v[56:57], v[104:105]
	v_mul_f32_e32 v56, v61, v61
	v_mul_f32_e32 v57, v63, v63
	v_fmac_f32_e32 v56, v60, v60
	v_fmac_f32_e32 v57, v62, v62
	v_add_f32_e32 v56, v56, v57
	v_mul_f32_e32 v57, v59, v59
	v_mul_f32_e32 v104, v107, v107
	v_fmac_f32_e32 v57, v58, v58
	v_fmac_f32_e32 v104, v106, v106
	v_lshlrev_b64 v[114:115], 10, v[144:145]
	v_add_f32_e32 v57, v57, v104
	v_lshl_add_u64 v[114:115], v[114:115], 0, v[180:181]
	v_add_f32_e32 v104, v56, v57
	v_cvt_pk_bf16_f32 v56, v60, v61
	v_cvt_pk_bf16_f32 v57, v62, v63
	s_waitcnt vmcnt(14)
	v_pk_add_f32 v[54:55], v[54:55], v[102:103]
	v_pk_add_f32 v[52:53], v[52:53], v[100:101]
	v_cvt_pk_bf16_f32 v58, v58, v59
	v_cvt_pk_bf16_f32 v59, v106, v107
	v_lshl_add_u64 v[60:61], v[114:115], 1, s[12:13]
	global_store_dwordx4 v[60:61], v[56:59], off sc1
	s_nop 1
	v_pk_add_f32 v[56:57], v[50:51], v[98:99]
	v_mul_f32_e32 v50, v53, v53
	v_mul_f32_e32 v51, v55, v55
	v_pk_add_f32 v[48:49], v[48:49], v[96:97]
	v_fmac_f32_e32 v50, v52, v52
	v_fmac_f32_e32 v51, v54, v54
	v_add_f32_e32 v50, v50, v51
	v_mul_f32_e32 v51, v49, v49
	v_mul_f32_e32 v58, v57, v57
	v_fmac_f32_e32 v51, v48, v48
	v_fmac_f32_e32 v58, v56, v56
	v_add_f32_e32 v51, v51, v58
	v_add_f32_e32 v50, v50, v51
	v_add_f32_e32 v58, v104, v50
	ds_bpermute_b32 v59, v197, v58
	v_cvt_pk_bf16_f32 v50, v52, v53
	v_cvt_pk_bf16_f32 v52, v48, v49
	v_cvt_pk_bf16_f32 v51, v54, v55
	v_cvt_pk_bf16_f32 v53, v56, v57
	s_waitcnt lgkmcnt(0)
	v_add_f32_e32 v48, v58, v59
	ds_bpermute_b32 v49, v198, v48
	v_lshl_add_u64 v[54:55], v[60:61], 0, s[14:15]
	global_store_dwordx4 v[54:55], v[50:53], off sc1
	s_nop 1
	s_and_saveexec_b64 s[0:1], s[6:7]
	s_cbranch_execz .LBB0_897
	s_waitcnt lgkmcnt(0)
	v_add_f32_e32 v50, v48, v49
	s_lshl_b32 s26, s51, 2
	v_lshlrev_b64 v[48:49], 6, v[144:145]
	s_ashr_i32 s27, s26, 31
	v_lshl_add_u64 v[48:49], s[18:19], 0, v[48:49]
	v_lshl_add_u64 v[48:49], s[26:27], 2, v[48:49]
	s_lshl_b32 s10, s45, 2
	v_lshl_add_u64 v[48:49], v[48:49], 0, s[10:11]
	global_store_dword v[48:49], v50, off sc1
.LBB0_897:
	s_or_b64 exec, exec, s[0:1]
	v_add_u32_e32 v96, 0xb0, v182
	v_ashrrev_i32_e32 v97, 31, v96
	s_waitcnt lgkmcnt(0)
	v_lshlrev_b64 v[48:49], 12, v[96:97]
	v_lshl_add_u64 v[52:53], v[184:185], 0, v[48:49]
	global_load_dwordx4 v[56:59], v[52:53], off offset:16
	global_load_dwordx4 v[60:63], v[52:53], off
	global_load_dwordx4 v[48:51], v[52:53], off offset:528
	s_nop 0
	global_load_dwordx4 v[52:55], v[52:53], off offset:512
	s_waitcnt vmcnt(14)
	v_pk_add_f32 v[46:47], v[46:47], v[94:95]
	v_pk_add_f32 v[44:45], v[44:45], v[92:93]
	v_pk_add_f32 v[90:91], v[42:43], v[90:91]
	v_pk_add_f32 v[42:43], v[40:41], v[88:89]
	v_mul_f32_e32 v40, v45, v45
	v_mul_f32_e32 v41, v47, v47
	v_fmac_f32_e32 v40, v44, v44
	v_fmac_f32_e32 v41, v46, v46
	v_add_f32_e32 v40, v40, v41
	v_mul_f32_e32 v41, v43, v43
	v_mul_f32_e32 v88, v91, v91
	v_fmac_f32_e32 v41, v42, v42
	v_fmac_f32_e32 v88, v90, v90
	v_lshlrev_b64 v[98:99], 10, v[128:129]
	v_add_f32_e32 v41, v41, v88
	v_lshl_add_u64 v[98:99], v[98:99], 0, v[180:181]
	v_add_f32_e32 v88, v40, v41
	v_cvt_pk_bf16_f32 v40, v44, v45
	v_cvt_pk_bf16_f32 v41, v46, v47
	s_waitcnt vmcnt(14)
	v_pk_add_f32 v[38:39], v[38:39], v[86:87]
	v_pk_add_f32 v[36:37], v[36:37], v[84:85]
	v_cvt_pk_bf16_f32 v42, v42, v43
	v_cvt_pk_bf16_f32 v43, v90, v91
	v_lshl_add_u64 v[44:45], v[98:99], 1, s[12:13]
	global_store_dwordx4 v[44:45], v[40:43], off sc1
	s_nop 1
	v_pk_add_f32 v[40:41], v[34:35], v[82:83]
	v_mul_f32_e32 v34, v37, v37
	v_mul_f32_e32 v35, v39, v39
	v_pk_add_f32 v[32:33], v[32:33], v[80:81]
	v_fmac_f32_e32 v34, v36, v36
	v_fmac_f32_e32 v35, v38, v38
	v_add_f32_e32 v34, v34, v35
	v_mul_f32_e32 v35, v33, v33
	v_mul_f32_e32 v42, v41, v41
	v_fmac_f32_e32 v35, v32, v32
	v_fmac_f32_e32 v42, v40, v40
	v_add_f32_e32 v35, v35, v42
	v_add_f32_e32 v34, v34, v35
	v_add_f32_e32 v42, v88, v34
	ds_bpermute_b32 v43, v197, v42
	v_cvt_pk_bf16_f32 v34, v36, v37
	v_cvt_pk_bf16_f32 v36, v32, v33
	v_cvt_pk_bf16_f32 v35, v38, v39
	v_cvt_pk_bf16_f32 v37, v40, v41
	s_waitcnt lgkmcnt(0)
	v_add_f32_e32 v32, v42, v43
	ds_bpermute_b32 v33, v198, v32
	v_lshl_add_u64 v[38:39], v[44:45], 0, s[14:15]
	global_store_dwordx4 v[38:39], v[34:37], off sc1
	s_nop 1
	s_and_saveexec_b64 s[0:1], s[6:7]
	s_cbranch_execz .LBB0_899
	s_waitcnt lgkmcnt(0)
	v_add_f32_e32 v34, v32, v33
	s_lshl_b32 s26, s51, 2
	v_lshlrev_b64 v[32:33], 6, v[128:129]
	s_ashr_i32 s27, s26, 31
	v_lshl_add_u64 v[32:33], s[18:19], 0, v[32:33]
	v_lshl_add_u64 v[32:33], s[26:27], 2, v[32:33]
	s_lshl_b32 s10, s45, 2
	v_lshl_add_u64 v[32:33], v[32:33], 0, s[10:11]
	global_store_dword v[32:33], v34, off sc1
.LBB0_899:
	s_or_b64 exec, exec, s[0:1]
	s_waitcnt vmcnt(10)
	v_pk_add_f32 v[30:31], v[30:31], v[78:79]
	v_pk_add_f32 v[28:29], v[28:29], v[76:77]
	v_pk_add_f32 v[34:35], v[26:27], v[74:75]
	v_pk_add_f32 v[26:27], v[24:25], v[72:73]
	v_mul_f32_e32 v24, v29, v29
	v_mul_f32_e32 v25, v31, v31
	v_fmac_f32_e32 v24, v28, v28
	v_fmac_f32_e32 v25, v30, v30
	v_add_f32_e32 v24, v24, v25
	v_mul_f32_e32 v25, v27, v27
	v_mul_f32_e32 v36, v35, v35
	v_fmac_f32_e32 v25, v26, v26
	v_fmac_f32_e32 v36, v34, v34
	s_waitcnt lgkmcnt(0)
	v_lshlrev_b64 v[32:33], 10, v[112:113]
	v_add_f32_e32 v25, v25, v36
	v_lshl_add_u64 v[32:33], v[32:33], 0, v[180:181]
	v_add_f32_e32 v36, v24, v25
	v_cvt_pk_bf16_f32 v24, v28, v29
	v_cvt_pk_bf16_f32 v25, v30, v31
	s_waitcnt vmcnt(10)
	v_pk_add_f32 v[22:23], v[22:23], v[70:71]
	v_pk_add_f32 v[20:21], v[20:21], v[68:69]
	v_cvt_pk_bf16_f32 v26, v26, v27
	v_cvt_pk_bf16_f32 v27, v34, v35
	v_lshl_add_u64 v[28:29], v[32:33], 1, s[12:13]
	global_store_dwordx4 v[28:29], v[24:27], off sc1
	s_nop 1
	v_pk_add_f32 v[24:25], v[18:19], v[66:67]
	v_mul_f32_e32 v18, v21, v21
	v_mul_f32_e32 v19, v23, v23
	v_pk_add_f32 v[16:17], v[16:17], v[64:65]
	v_fmac_f32_e32 v18, v20, v20
	v_fmac_f32_e32 v19, v22, v22
	v_add_f32_e32 v18, v18, v19
	v_mul_f32_e32 v19, v17, v17
	v_mul_f32_e32 v26, v25, v25
	v_fmac_f32_e32 v19, v16, v16
	v_fmac_f32_e32 v26, v24, v24
	v_add_f32_e32 v19, v19, v26
	v_add_f32_e32 v18, v18, v19
	v_add_f32_e32 v26, v36, v18
	ds_bpermute_b32 v27, v197, v26
	v_cvt_pk_bf16_f32 v18, v20, v21
	v_cvt_pk_bf16_f32 v20, v16, v17
	v_cvt_pk_bf16_f32 v19, v22, v23
	v_cvt_pk_bf16_f32 v21, v24, v25
	s_waitcnt lgkmcnt(0)
	v_add_f32_e32 v16, v26, v27
	ds_bpermute_b32 v17, v198, v16
	v_lshl_add_u64 v[22:23], v[28:29], 0, s[14:15]
	global_store_dwordx4 v[22:23], v[18:21], off sc1
	s_nop 1
	s_and_saveexec_b64 s[0:1], s[6:7]
	s_cbranch_execz .LBB0_901
	s_waitcnt lgkmcnt(0)
	v_add_f32_e32 v18, v16, v17
	s_lshl_b32 s26, s51, 2
	v_lshlrev_b64 v[16:17], 6, v[112:113]
	s_ashr_i32 s27, s26, 31
	v_lshl_add_u64 v[16:17], s[18:19], 0, v[16:17]
	v_lshl_add_u64 v[16:17], s[26:27], 2, v[16:17]
	s_lshl_b32 s10, s45, 2
	v_lshl_add_u64 v[16:17], v[16:17], 0, s[10:11]
	global_store_dword v[16:17], v18, off sc1
.LBB0_901:
	s_or_b64 exec, exec, s[0:1]
	s_waitcnt vmcnt(6)
	v_pk_add_f32 v[14:15], v[14:15], v[62:63]
	v_pk_add_f32 v[12:13], v[12:13], v[60:61]
	v_pk_add_f32 v[18:19], v[10:11], v[58:59]
	v_pk_add_f32 v[10:11], v[8:9], v[56:57]
	v_mul_f32_e32 v8, v13, v13
	v_mul_f32_e32 v9, v15, v15
	v_fmac_f32_e32 v8, v12, v12
	v_fmac_f32_e32 v9, v14, v14
	v_add_f32_e32 v8, v8, v9
	v_mul_f32_e32 v9, v11, v11
	v_mul_f32_e32 v20, v19, v19
	v_fmac_f32_e32 v9, v10, v10
	v_fmac_f32_e32 v20, v18, v18
	s_waitcnt lgkmcnt(0)
	v_lshlrev_b64 v[16:17], 10, v[96:97]
	v_add_f32_e32 v9, v9, v20
	v_lshl_add_u64 v[16:17], v[16:17], 0, v[180:181]
	v_add_f32_e32 v20, v8, v9
	v_cvt_pk_bf16_f32 v8, v12, v13
	v_cvt_pk_bf16_f32 v9, v14, v15
	s_waitcnt vmcnt(6)
	v_pk_add_f32 v[6:7], v[6:7], v[54:55]
	v_pk_add_f32 v[4:5], v[4:5], v[52:53]
	v_cvt_pk_bf16_f32 v10, v10, v11
	v_cvt_pk_bf16_f32 v11, v18, v19
	v_lshl_add_u64 v[12:13], v[16:17], 1, s[12:13]
	global_store_dwordx4 v[12:13], v[8:11], off sc1
	s_nop 1
	v_pk_add_f32 v[8:9], v[2:3], v[50:51]
	v_mul_f32_e32 v2, v5, v5
	v_mul_f32_e32 v3, v7, v7
	v_pk_add_f32 v[0:1], v[0:1], v[48:49]
	v_fmac_f32_e32 v2, v4, v4
	v_fmac_f32_e32 v3, v6, v6
	v_add_f32_e32 v2, v2, v3
	v_mul_f32_e32 v3, v1, v1
	v_mul_f32_e32 v10, v9, v9
	v_fmac_f32_e32 v3, v0, v0
	v_fmac_f32_e32 v10, v8, v8
	v_add_f32_e32 v3, v3, v10
	v_add_f32_e32 v2, v2, v3
	v_add_f32_e32 v10, v20, v2
	ds_bpermute_b32 v11, v197, v10
	v_cvt_pk_bf16_f32 v2, v4, v5
	v_cvt_pk_bf16_f32 v4, v0, v1
	v_cvt_pk_bf16_f32 v3, v6, v7
	v_cvt_pk_bf16_f32 v5, v8, v9
	s_waitcnt lgkmcnt(0)
	v_add_f32_e32 v0, v10, v11
	ds_bpermute_b32 v1, v198, v0
	v_lshl_add_u64 v[6:7], v[12:13], 0, s[14:15]
	global_store_dwordx4 v[6:7], v[2:5], off sc1
	s_nop 1
	s_and_saveexec_b64 s[0:1], s[6:7]
	s_cbranch_execz .LBB0_903
	s_waitcnt lgkmcnt(0)
	v_add_f32_e32 v2, v0, v1
	s_lshl_b32 s26, s51, 2
	v_lshlrev_b64 v[0:1], 6, v[96:97]
	s_ashr_i32 s27, s26, 31
	v_lshl_add_u64 v[0:1], s[18:19], 0, v[0:1]
	v_lshl_add_u64 v[0:1], s[26:27], 2, v[0:1]
	s_lshl_b32 s10, s45, 2
	v_lshl_add_u64 v[0:1], v[0:1], 0, s[10:11]
	global_store_dword v[0:1], v2, off sc1

.LBB0_1097:
	v_lshl_add_u32 v202, s24, 8, v171
	v_lshl_or_b32 v128, s47, 8, v213
	v_ashrrev_i32_e32 v203, 31, v202
	v_lshlrev_b64 v[130:131], 11, v[202:203]
	v_ashrrev_i32_e32 v129, 31, v128
	v_lshl_add_u64 v[130:131], s[12:13], 0, v[130:131]
	v_lshlrev_b64 v[204:205], 1, v[128:129]
	v_lshl_add_u64 v[226:227], v[130:131], 0, v[204:205]
	global_load_dwordx4 v[218:221], v[226:227], off
	global_load_dwordx4 v[222:225], v[226:227], off offset:256
	v_or_b32_e32 v208, 16, v202
	v_or_b32_e32 v200, 32, v202
	v_or_b32_e32 v196, 48, v202
	v_add_u32_e32 v192, 0x80, v202
	v_add_u32_e32 v188, 0x90, v202
	v_ashrrev_i32_e32 v209, 31, v208
	v_ashrrev_i32_e32 v201, 31, v200
	v_ashrrev_i32_e32 v197, 31, v196
	v_ashrrev_i32_e32 v193, 31, v192
	v_ashrrev_i32_e32 v189, 31, v188
	v_lshlrev_b64 v[128:129], 11, v[208:209]
	v_lshlrev_b64 v[130:131], 11, v[200:201]
	v_lshlrev_b64 v[132:133], 11, v[196:197]
	v_lshlrev_b64 v[134:135], 11, v[192:193]
	v_lshlrev_b64 v[136:137], 11, v[188:189]
	v_lshl_add_u64 v[128:129], s[12:13], 0, v[128:129]
	v_lshl_add_u64 v[130:131], s[12:13], 0, v[130:131]
	v_lshl_add_u64 v[132:133], s[12:13], 0, v[132:133]
	v_lshl_add_u64 v[134:135], s[12:13], 0, v[134:135]
	v_lshl_add_u64 v[136:137], s[12:13], 0, v[136:137]
	v_lshl_add_u64 v[210:211], v[128:129], 0, v[204:205]
	v_lshl_add_u64 v[206:207], v[130:131], 0, v[204:205]
	v_lshl_add_u64 v[198:199], v[132:133], 0, v[204:205]
	v_lshl_add_u64 v[194:195], v[134:135], 0, v[204:205]
	v_lshl_add_u64 v[190:191], v[136:137], 0, v[204:205]
	global_load_dwordx4 v[164:167], v[210:211], off
	global_load_dwordx4 v[160:163], v[210:211], off offset:256
	global_load_dwordx4 v[156:159], v[206:207], off
	global_load_dwordx4 v[152:155], v[206:207], off offset:256
	global_load_dwordx4 v[148:151], v[198:199], off
	global_load_dwordx4 v[144:147], v[198:199], off offset:256
	global_load_dwordx4 v[140:143], v[194:195], off
	global_load_dwordx4 v[136:139], v[194:195], off offset:256
	global_load_dwordx4 v[132:135], v[190:191], off
	global_load_dwordx4 v[128:131], v[190:191], off offset:256
	v_lshl_add_u64 v[228:229], v[226:227], 0, s[14:15]
	s_waitcnt vmcnt(8)
	v_lshlrev_b32_e32 v230, 16, v218
	v_and_b32_e32 v231, 0xffff0000, v218
	v_lshlrev_b32_e32 v218, 16, v219
	v_and_b32_e32 v219, 0xffff0000, v219
	v_lshlrev_b32_e32 v232, 16, v220
	v_and_b32_e32 v233, 0xffff0000, v220
	v_lshlrev_b32_e32 v220, 16, v221
	v_and_b32_e32 v221, 0xffff0000, v221
	v_lshlrev_b32_e32 v234, 16, v222
	v_and_b32_e32 v235, 0xffff0000, v222
	v_lshlrev_b32_e32 v222, 16, v223
	v_and_b32_e32 v223, 0xffff0000, v223
	v_lshlrev_b32_e32 v236, 16, v224
	v_and_b32_e32 v237, 0xffff0000, v224
	v_lshlrev_b32_e32 v224, 16, v225
	v_and_b32_e32 v225, 0xffff0000, v225
	v_pk_add_f32 v[126:127], v[126:127], v[218:219]
	v_pk_add_f32 v[124:125], v[124:125], v[230:231]
	v_pk_add_f32 v[122:123], v[122:123], v[220:221]
	v_pk_add_f32 v[120:121], v[120:121], v[232:233]
	v_pk_add_f32 v[118:119], v[118:119], v[222:223]
	v_pk_add_f32 v[218:219], v[114:115], v[224:225]
	v_mul_f32_e32 v222, v125, v125
	v_mul_f32_e32 v223, v127, v127
	v_mul_f32_e32 v224, v121, v121
	v_mul_f32_e32 v225, v123, v123
	v_pk_add_f32 v[220:221], v[112:113], v[236:237]
	v_cvt_pk_bf16_f32 v112, v124, v125
	v_cvt_pk_bf16_f32 v113, v126, v127
	v_fmac_f32_e32 v222, v124, v124
	v_fmac_f32_e32 v223, v126, v126
	v_fmac_f32_e32 v224, v120, v120
	v_fmac_f32_e32 v225, v122, v122
	v_pk_add_f32 v[116:117], v[116:117], v[234:235]
	v_cvt_pk_bf16_f32 v114, v120, v121
	v_cvt_pk_bf16_f32 v115, v122, v123
	global_store_dwordx4 v[226:227], v[112:115], off sc1
	s_nop 1
	v_add_f32_e32 v112, v222, v223
	v_add_f32_e32 v113, v224, v225
	v_mul_f32_e32 v121, v117, v117
	v_mul_f32_e32 v123, v119, v119
	v_add_f32_e32 v112, v112, v113
	v_mul_f32_e32 v113, v221, v221
	v_mul_f32_e32 v115, v219, v219
	v_fmac_f32_e32 v121, v116, v116
	v_fmac_f32_e32 v123, v118, v118
	v_fmac_f32_e32 v113, v220, v220
	v_fmac_f32_e32 v115, v218, v218
	v_add_f32_e32 v114, v121, v123
	v_add_f32_e32 v113, v113, v115
	v_add_f32_e32 v113, v114, v113
	v_and_b32_e32 v114, 64, v217
	v_add_f32_e32 v112, v112, v113
	v_xor_b32_e32 v113, 16, v217
	v_add_u32_e32 v121, 64, v114
	v_cmp_lt_i32_e32 vcc, v113, v121
	v_cvt_pk_bf16_f32 v114, v116, v117
	v_cvt_pk_bf16_f32 v115, v118, v119
	v_cndmask_b32_e32 v113, v217, v113, vcc
	v_lshlrev_b32_e32 v120, 2, v113
	ds_bpermute_b32 v113, v120, v112
	v_cvt_pk_bf16_f32 v116, v220, v221
	v_cvt_pk_bf16_f32 v117, v218, v219
	global_store_dwordx4 v[228:229], v[114:117], off sc1
	s_nop 1
	s_waitcnt lgkmcnt(0)
	v_add_f32_e32 v112, v112, v113
	v_xor_b32_e32 v113, 32, v217
	v_cmp_lt_i32_e32 vcc, v113, v121
	s_nop 1
	v_cndmask_b32_e32 v113, v217, v113, vcc
	v_lshlrev_b32_e32 v121, 2, v113
	ds_bpermute_b32 v113, v121, v112
	s_and_saveexec_b64 s[0:1], s[6:7]
	s_cbranch_execz .LBB0_1099
	s_waitcnt lgkmcnt(0)
	v_add_f32_e32 v114, v112, v113
	s_lshl_b32 s24, s47, 2
	v_lshlrev_b64 v[112:113], 6, v[202:203]
	s_ashr_i32 s25, s24, 31
	v_lshl_add_u64 v[112:113], s[16:17], 0, v[112:113]
	v_lshl_add_u64 v[112:113], s[24:25], 2, v[112:113]
	s_lshl_b32 s4, s41, 2
	v_lshl_add_u64 v[112:113], v[112:113], 0, s[4:5]
	global_store_dword v[112:113], v114, off sc1
.LBB0_1099:
	s_or_b64 exec, exec, s[0:1]
	v_lshlrev_b32_e32 v114, 16, v164
	v_and_b32_e32 v115, 0xffff0000, v164
	v_lshlrev_b32_e32 v116, 16, v165
	v_and_b32_e32 v117, 0xffff0000, v165
	v_lshlrev_b32_e32 v118, 16, v166
	v_and_b32_e32 v119, 0xffff0000, v166
	v_lshlrev_b32_e32 v122, 16, v167
	v_and_b32_e32 v123, 0xffff0000, v167
	v_pk_add_f32 v[110:111], v[110:111], v[116:117]
	v_pk_add_f32 v[108:109], v[108:109], v[114:115]
	v_pk_add_f32 v[114:115], v[106:107], v[122:123]
	v_pk_add_f32 v[106:107], v[104:105], v[118:119]
	v_mul_f32_e32 v104, v109, v109
	v_mul_f32_e32 v105, v111, v111
	v_fmac_f32_e32 v104, v108, v108
	v_fmac_f32_e32 v105, v110, v110
	v_add_f32_e32 v104, v104, v105
	v_mul_f32_e32 v105, v107, v107
	v_mul_f32_e32 v116, v115, v115
	v_fmac_f32_e32 v105, v106, v106
	v_fmac_f32_e32 v116, v114, v114
	v_lshlrev_b32_e32 v124, 16, v160
	v_and_b32_e32 v125, 0xffff0000, v160
	v_lshlrev_b32_e32 v126, 16, v161
	v_and_b32_e32 v127, 0xffff0000, v161
	v_add_f32_e32 v105, v105, v116
	v_lshlrev_b32_e32 v160, 16, v162
	v_and_b32_e32 v161, 0xffff0000, v162
	v_lshlrev_b32_e32 v162, 16, v163
	v_and_b32_e32 v163, 0xffff0000, v163
	v_add_f32_e32 v116, v104, v105
	v_cvt_pk_bf16_f32 v104, v108, v109
	v_cvt_pk_bf16_f32 v105, v110, v111
	v_pk_add_f32 v[102:103], v[102:103], v[126:127]
	v_pk_add_f32 v[100:101], v[100:101], v[124:125]
	v_cvt_pk_bf16_f32 v106, v106, v107
	v_cvt_pk_bf16_f32 v107, v114, v115
	global_store_dwordx4 v[210:211], v[104:107], off sc1
	s_nop 1
	v_pk_add_f32 v[104:105], v[98:99], v[162:163]
	v_mul_f32_e32 v98, v101, v101
	v_mul_f32_e32 v99, v103, v103
	v_pk_add_f32 v[96:97], v[96:97], v[160:161]
	v_fmac_f32_e32 v98, v100, v100
	v_fmac_f32_e32 v99, v102, v102
	v_add_f32_e32 v98, v98, v99
	v_mul_f32_e32 v99, v97, v97
	v_mul_f32_e32 v106, v105, v105
	v_fmac_f32_e32 v99, v96, v96
	v_fmac_f32_e32 v106, v104, v104
	v_add_f32_e32 v99, v99, v106
	v_add_f32_e32 v98, v98, v99
	v_add_f32_e32 v106, v116, v98
	ds_bpermute_b32 v107, v120, v106
	v_cvt_pk_bf16_f32 v98, v100, v101
	v_cvt_pk_bf16_f32 v100, v96, v97
	s_waitcnt lgkmcnt(1)
	v_lshl_add_u64 v[112:113], v[210:211], 0, s[14:15]
	v_cvt_pk_bf16_f32 v99, v102, v103
	s_waitcnt lgkmcnt(0)
	v_add_f32_e32 v96, v106, v107
	ds_bpermute_b32 v97, v121, v96
	v_cvt_pk_bf16_f32 v101, v104, v105
	global_store_dwordx4 v[112:113], v[98:101], off sc1
	s_nop 1
	s_and_saveexec_b64 s[0:1], s[6:7]
	s_cbranch_execz .LBB0_1101
	s_waitcnt lgkmcnt(0)
	v_add_f32_e32 v98, v96, v97
	s_lshl_b32 s24, s47, 2
	v_lshlrev_b64 v[96:97], 6, v[208:209]
	s_ashr_i32 s25, s24, 31
	v_lshl_add_u64 v[96:97], s[16:17], 0, v[96:97]
	v_lshl_add_u64 v[96:97], s[24:25], 2, v[96:97]
	s_lshl_b32 s4, s41, 2
	v_lshl_add_u64 v[96:97], v[96:97], 0, s[4:5]
	global_store_dword v[96:97], v98, off sc1
.LBB0_1101:
	s_or_b64 exec, exec, s[0:1]
	v_add_u32_e32 v116, 0xa0, v202
	v_ashrrev_i32_e32 v117, 31, v116
	s_waitcnt lgkmcnt(0)
	v_lshlrev_b64 v[96:97], 11, v[116:117]
	v_add_u32_e32 v112, 0xb0, v202
	v_lshl_add_u64 v[96:97], s[12:13], 0, v[96:97]
	v_ashrrev_i32_e32 v113, 31, v112
	v_lshl_add_u64 v[118:119], v[96:97], 0, v[204:205]
	v_lshlrev_b64 v[96:97], 11, v[112:113]
	v_lshl_add_u64 v[96:97], s[12:13], 0, v[96:97]
	v_lshl_add_u64 v[114:115], v[96:97], 0, v[204:205]
	global_load_dwordx4 v[108:111], v[118:119], off
	global_load_dwordx4 v[104:107], v[118:119], off offset:256
	global_load_dwordx4 v[100:103], v[114:115], off
	global_load_dwordx4 v[96:99], v[114:115], off offset:256
	s_waitcnt vmcnt(14)
	v_lshlrev_b32_e32 v124, 16, v156
	v_and_b32_e32 v125, 0xffff0000, v156
	v_lshlrev_b32_e32 v126, 16, v157
	v_and_b32_e32 v127, 0xffff0000, v157
	v_lshlrev_b32_e32 v156, 16, v158
	v_and_b32_e32 v157, 0xffff0000, v158
	v_lshlrev_b32_e32 v158, 16, v159
	v_and_b32_e32 v159, 0xffff0000, v159
	v_pk_add_f32 v[94:95], v[94:95], v[126:127]
	v_pk_add_f32 v[92:93], v[92:93], v[124:125]
	v_pk_add_f32 v[124:125], v[90:91], v[158:159]
	v_pk_add_f32 v[90:91], v[88:89], v[156:157]
	v_mul_f32_e32 v88, v93, v93
	v_mul_f32_e32 v89, v95, v95
	v_fmac_f32_e32 v88, v92, v92
	v_fmac_f32_e32 v89, v94, v94
	v_add_f32_e32 v88, v88, v89
	v_mul_f32_e32 v89, v91, v91
	v_mul_f32_e32 v126, v125, v125
	v_fmac_f32_e32 v89, v90, v90
	v_fmac_f32_e32 v126, v124, v124
	v_lshlrev_b32_e32 v160, 16, v152
	v_and_b32_e32 v161, 0xffff0000, v152
	v_lshlrev_b32_e32 v152, 16, v153
	v_and_b32_e32 v153, 0xffff0000, v153
	v_add_f32_e32 v89, v89, v126
	v_lshlrev_b32_e32 v162, 16, v154
	v_and_b32_e32 v163, 0xffff0000, v154
	v_lshlrev_b32_e32 v154, 16, v155
	v_and_b32_e32 v155, 0xffff0000, v155
	v_add_f32_e32 v126, v88, v89
	v_cvt_pk_bf16_f32 v88, v92, v93
	v_cvt_pk_bf16_f32 v89, v94, v95
	v_pk_add_f32 v[86:87], v[86:87], v[152:153]
	v_pk_add_f32 v[84:85], v[84:85], v[160:161]
	v_cvt_pk_bf16_f32 v90, v90, v91
	v_cvt_pk_bf16_f32 v91, v124, v125
	global_store_dwordx4 v[206:207], v[88:91], off sc1
	s_nop 1
	v_pk_add_f32 v[88:89], v[82:83], v[154:155]
	v_mul_f32_e32 v82, v85, v85
	v_mul_f32_e32 v83, v87, v87
	v_pk_add_f32 v[80:81], v[80:81], v[162:163]
	v_fmac_f32_e32 v82, v84, v84
	v_fmac_f32_e32 v83, v86, v86
	v_add_f32_e32 v82, v82, v83
	v_mul_f32_e32 v83, v81, v81
	v_mul_f32_e32 v90, v89, v89
	v_fmac_f32_e32 v83, v80, v80
	v_fmac_f32_e32 v90, v88, v88
	v_add_f32_e32 v83, v83, v90
	v_add_f32_e32 v82, v82, v83
	v_add_f32_e32 v90, v126, v82
	ds_bpermute_b32 v91, v120, v90
	v_cvt_pk_bf16_f32 v82, v84, v85
	v_cvt_pk_bf16_f32 v84, v80, v81
	v_lshl_add_u64 v[122:123], v[206:207], 0, s[14:15]
	v_cvt_pk_bf16_f32 v83, v86, v87
	s_waitcnt lgkmcnt(0)
	v_add_f32_e32 v80, v90, v91
	ds_bpermute_b32 v81, v121, v80
	v_cvt_pk_bf16_f32 v85, v88, v89
	global_store_dwordx4 v[122:123], v[82:85], off sc1
	s_nop 1
	s_and_saveexec_b64 s[0:1], s[6:7]
	s_cbranch_execz .LBB0_1103
	s_waitcnt lgkmcnt(0)
	v_add_f32_e32 v82, v80, v81
	s_lshl_b32 s24, s47, 2
	v_lshlrev_b64 v[80:81], 6, v[200:201]
	s_ashr_i32 s25, s24, 31
	v_lshl_add_u64 v[80:81], s[16:17], 0, v[80:81]
	v_lshl_add_u64 v[80:81], s[24:25], 2, v[80:81]
	s_lshl_b32 s4, s41, 2
	v_lshl_add_u64 v[80:81], v[80:81], 0, s[4:5]
	global_store_dword v[80:81], v82, off sc1
.LBB0_1103:
	s_or_b64 exec, exec, s[0:1]
	v_lshlrev_b32_e32 v82, 16, v148
	v_and_b32_e32 v83, 0xffff0000, v148
	v_lshlrev_b32_e32 v84, 16, v149
	v_and_b32_e32 v85, 0xffff0000, v149
	v_lshlrev_b32_e32 v86, 16, v150
	v_and_b32_e32 v87, 0xffff0000, v150
	v_lshlrev_b32_e32 v88, 16, v151
	v_and_b32_e32 v89, 0xffff0000, v151
	v_pk_add_f32 v[78:79], v[78:79], v[84:85]
	v_pk_add_f32 v[76:77], v[76:77], v[82:83]
	v_pk_add_f32 v[82:83], v[74:75], v[88:89]
	v_pk_add_f32 v[74:75], v[72:73], v[86:87]
	v_mul_f32_e32 v72, v77, v77
	v_mul_f32_e32 v73, v79, v79
	v_fmac_f32_e32 v72, v76, v76
	v_fmac_f32_e32 v73, v78, v78
	v_add_f32_e32 v72, v72, v73
	v_mul_f32_e32 v73, v75, v75
	v_mul_f32_e32 v84, v83, v83
	v_fmac_f32_e32 v73, v74, v74
	v_fmac_f32_e32 v84, v82, v82
	v_lshlrev_b32_e32 v90, 16, v144
	v_and_b32_e32 v91, 0xffff0000, v144
	v_lshlrev_b32_e32 v92, 16, v145
	v_and_b32_e32 v93, 0xffff0000, v145
	v_add_f32_e32 v73, v73, v84
	v_lshlrev_b32_e32 v122, 16, v147
	v_and_b32_e32 v123, 0xffff0000, v147
	v_add_f32_e32 v84, v72, v73
	v_cvt_pk_bf16_f32 v72, v76, v77
	v_cvt_pk_bf16_f32 v73, v78, v79
	v_pk_add_f32 v[70:71], v[70:71], v[92:93]
	v_pk_add_f32 v[68:69], v[68:69], v[90:91]
	v_lshlrev_b32_e32 v94, 16, v146
	v_and_b32_e32 v95, 0xffff0000, v146
	v_cvt_pk_bf16_f32 v74, v74, v75
	v_cvt_pk_bf16_f32 v75, v82, v83
	global_store_dwordx4 v[198:199], v[72:75], off sc1
	s_nop 1
	v_pk_add_f32 v[72:73], v[66:67], v[122:123]
	v_mul_f32_e32 v66, v69, v69
	v_mul_f32_e32 v67, v71, v71
	v_pk_add_f32 v[64:65], v[64:65], v[94:95]
	v_fmac_f32_e32 v66, v68, v68
	v_fmac_f32_e32 v67, v70, v70
	v_add_f32_e32 v66, v66, v67
	v_mul_f32_e32 v67, v65, v65
	v_mul_f32_e32 v74, v73, v73
	v_fmac_f32_e32 v67, v64, v64
	v_fmac_f32_e32 v74, v72, v72
	v_add_f32_e32 v67, v67, v74
	v_add_f32_e32 v66, v66, v67
	v_add_f32_e32 v74, v84, v66
	ds_bpermute_b32 v75, v120, v74
	v_cvt_pk_bf16_f32 v66, v68, v69
	v_cvt_pk_bf16_f32 v68, v64, v65
	s_waitcnt lgkmcnt(1)
	v_lshl_add_u64 v[80:81], v[198:199], 0, s[14:15]
	v_cvt_pk_bf16_f32 v67, v70, v71
	s_waitcnt lgkmcnt(0)
	v_add_f32_e32 v64, v74, v75
	ds_bpermute_b32 v65, v121, v64
	v_cvt_pk_bf16_f32 v69, v72, v73
	global_store_dwordx4 v[80:81], v[66:69], off sc1
	s_nop 1
	s_and_saveexec_b64 s[0:1], s[6:7]
	s_cbranch_execz .LBB0_1105
	s_waitcnt lgkmcnt(0)
	v_add_f32_e32 v66, v64, v65
	s_lshl_b32 s24, s47, 2
	v_lshlrev_b64 v[64:65], 6, v[196:197]
	s_ashr_i32 s25, s24, 31
	v_lshl_add_u64 v[64:65], s[16:17], 0, v[64:65]
	v_lshl_add_u64 v[64:65], s[24:25], 2, v[64:65]
	s_lshl_b32 s4, s41, 2
	v_lshl_add_u64 v[64:65], v[64:65], 0, s[4:5]
	global_store_dword v[64:65], v66, off sc1
.LBB0_1105:
	s_or_b64 exec, exec, s[0:1]
	s_waitcnt vmcnt(16)
	v_lshlrev_b32_e32 v66, 16, v140
	v_and_b32_e32 v67, 0xffff0000, v140
	v_lshlrev_b32_e32 v68, 16, v141
	v_and_b32_e32 v69, 0xffff0000, v141
	v_lshlrev_b32_e32 v70, 16, v142
	v_and_b32_e32 v71, 0xffff0000, v142
	v_lshlrev_b32_e32 v72, 16, v143
	v_and_b32_e32 v73, 0xffff0000, v143
	v_pk_add_f32 v[62:63], v[62:63], v[68:69]
	v_pk_add_f32 v[60:61], v[60:61], v[66:67]
	v_pk_add_f32 v[66:67], v[58:59], v[72:73]
	v_pk_add_f32 v[58:59], v[56:57], v[70:71]
	v_mul_f32_e32 v56, v61, v61
	v_mul_f32_e32 v57, v63, v63
	v_fmac_f32_e32 v56, v60, v60
	v_fmac_f32_e32 v57, v62, v62
	v_add_f32_e32 v56, v56, v57
	v_mul_f32_e32 v57, v59, v59
	v_mul_f32_e32 v68, v67, v67
	v_fmac_f32_e32 v57, v58, v58
	v_fmac_f32_e32 v68, v66, v66
	v_lshlrev_b32_e32 v74, 16, v136
	v_and_b32_e32 v75, 0xffff0000, v136
	v_lshlrev_b32_e32 v76, 16, v137
	v_and_b32_e32 v77, 0xffff0000, v137
	v_add_f32_e32 v57, v57, v68
	v_lshlrev_b32_e32 v80, 16, v139
	v_and_b32_e32 v81, 0xffff0000, v139
	v_add_f32_e32 v68, v56, v57
	v_cvt_pk_bf16_f32 v56, v60, v61
	v_cvt_pk_bf16_f32 v57, v62, v63
	v_pk_add_f32 v[54:55], v[54:55], v[76:77]
	v_pk_add_f32 v[52:53], v[52:53], v[74:75]
	v_lshlrev_b32_e32 v78, 16, v138
	v_and_b32_e32 v79, 0xffff0000, v138
	v_cvt_pk_bf16_f32 v58, v58, v59
	v_cvt_pk_bf16_f32 v59, v66, v67
	global_store_dwordx4 v[194:195], v[56:59], off sc1
	s_nop 1
	v_pk_add_f32 v[56:57], v[50:51], v[80:81]
	v_mul_f32_e32 v50, v53, v53
	v_mul_f32_e32 v51, v55, v55
	v_pk_add_f32 v[48:49], v[48:49], v[78:79]
	v_fmac_f32_e32 v50, v52, v52
	v_fmac_f32_e32 v51, v54, v54
	v_add_f32_e32 v50, v50, v51
	v_mul_f32_e32 v51, v49, v49
	v_mul_f32_e32 v58, v57, v57
	v_fmac_f32_e32 v51, v48, v48
	v_fmac_f32_e32 v58, v56, v56
	v_add_f32_e32 v51, v51, v58
	v_add_f32_e32 v50, v50, v51
	v_add_f32_e32 v58, v68, v50
	ds_bpermute_b32 v59, v120, v58
	v_cvt_pk_bf16_f32 v50, v52, v53
	v_cvt_pk_bf16_f32 v52, v48, v49
	s_waitcnt lgkmcnt(1)
	v_lshl_add_u64 v[64:65], v[194:195], 0, s[14:15]
	v_cvt_pk_bf16_f32 v51, v54, v55
	s_waitcnt lgkmcnt(0)
	v_add_f32_e32 v48, v58, v59
	ds_bpermute_b32 v49, v121, v48
	v_cvt_pk_bf16_f32 v53, v56, v57
	global_store_dwordx4 v[64:65], v[50:53], off sc1
	s_nop 1
	s_and_saveexec_b64 s[0:1], s[6:7]
	s_cbranch_execz .LBB0_1107
	s_waitcnt lgkmcnt(0)
	v_add_f32_e32 v50, v48, v49
	s_lshl_b32 s24, s47, 2
	v_lshlrev_b64 v[48:49], 6, v[192:193]
	s_ashr_i32 s25, s24, 31
	v_lshl_add_u64 v[48:49], s[16:17], 0, v[48:49]
	v_lshl_add_u64 v[48:49], s[24:25], 2, v[48:49]
	s_lshl_b32 s4, s41, 2
	v_lshl_add_u64 v[48:49], v[48:49], 0, s[4:5]
	global_store_dword v[48:49], v50, off sc1
.LBB0_1107:
	s_or_b64 exec, exec, s[0:1]
	v_lshlrev_b32_e32 v50, 16, v132
	v_and_b32_e32 v51, 0xffff0000, v132
	v_lshlrev_b32_e32 v52, 16, v133
	v_and_b32_e32 v53, 0xffff0000, v133
	v_lshlrev_b32_e32 v54, 16, v134
	v_and_b32_e32 v55, 0xffff0000, v134
	v_lshlrev_b32_e32 v56, 16, v135
	v_and_b32_e32 v57, 0xffff0000, v135
	v_pk_add_f32 v[46:47], v[46:47], v[52:53]
	v_pk_add_f32 v[44:45], v[44:45], v[50:51]
	v_pk_add_f32 v[50:51], v[42:43], v[56:57]
	v_pk_add_f32 v[42:43], v[40:41], v[54:55]
	v_mul_f32_e32 v40, v45, v45
	v_mul_f32_e32 v41, v47, v47
	v_fmac_f32_e32 v40, v44, v44
	v_fmac_f32_e32 v41, v46, v46
	v_add_f32_e32 v40, v40, v41
	v_mul_f32_e32 v41, v43, v43
	v_mul_f32_e32 v52, v51, v51
	v_fmac_f32_e32 v41, v42, v42
	v_fmac_f32_e32 v52, v50, v50
	v_lshlrev_b32_e32 v58, 16, v128
	v_and_b32_e32 v59, 0xffff0000, v128
	v_lshlrev_b32_e32 v60, 16, v129
	v_and_b32_e32 v61, 0xffff0000, v129
	v_add_f32_e32 v41, v41, v52
	v_lshlrev_b32_e32 v64, 16, v131
	v_and_b32_e32 v65, 0xffff0000, v131
	v_add_f32_e32 v52, v40, v41
	v_cvt_pk_bf16_f32 v40, v44, v45
	v_cvt_pk_bf16_f32 v41, v46, v47
	v_pk_add_f32 v[38:39], v[38:39], v[60:61]
	v_pk_add_f32 v[36:37], v[36:37], v[58:59]
	v_lshlrev_b32_e32 v62, 16, v130
	v_and_b32_e32 v63, 0xffff0000, v130
	v_cvt_pk_bf16_f32 v42, v42, v43
	v_cvt_pk_bf16_f32 v43, v50, v51
	global_store_dwordx4 v[190:191], v[40:43], off sc1
	s_nop 1
	v_pk_add_f32 v[40:41], v[34:35], v[64:65]
	v_mul_f32_e32 v34, v37, v37
	v_mul_f32_e32 v35, v39, v39
	v_pk_add_f32 v[32:33], v[32:33], v[62:63]
	v_fmac_f32_e32 v34, v36, v36
	v_fmac_f32_e32 v35, v38, v38
	v_add_f32_e32 v34, v34, v35
	v_mul_f32_e32 v35, v33, v33
	v_mul_f32_e32 v42, v41, v41
	v_fmac_f32_e32 v35, v32, v32
	v_fmac_f32_e32 v42, v40, v40
	v_add_f32_e32 v35, v35, v42
	v_add_f32_e32 v34, v34, v35
	v_add_f32_e32 v42, v52, v34
	ds_bpermute_b32 v43, v120, v42
	v_cvt_pk_bf16_f32 v34, v36, v37
	v_cvt_pk_bf16_f32 v36, v32, v33
	s_waitcnt lgkmcnt(1)
	v_lshl_add_u64 v[48:49], v[190:191], 0, s[14:15]
	v_cvt_pk_bf16_f32 v35, v38, v39
	s_waitcnt lgkmcnt(0)
	v_add_f32_e32 v32, v42, v43
	ds_bpermute_b32 v33, v121, v32
	v_cvt_pk_bf16_f32 v37, v40, v41
	global_store_dwordx4 v[48:49], v[34:37], off sc1
	s_nop 1
	s_and_saveexec_b64 s[0:1], s[6:7]
	s_cbranch_execz .LBB0_1109
	s_waitcnt lgkmcnt(0)
	v_add_f32_e32 v34, v32, v33
	s_lshl_b32 s24, s47, 2
	v_lshlrev_b64 v[32:33], 6, v[188:189]
	s_ashr_i32 s25, s24, 31
	v_lshl_add_u64 v[32:33], s[16:17], 0, v[32:33]
	v_lshl_add_u64 v[32:33], s[24:25], 2, v[32:33]
	s_lshl_b32 s4, s41, 2
	v_lshl_add_u64 v[32:33], v[32:33], 0, s[4:5]
	global_store_dword v[32:33], v34, off sc1
.LBB0_1109:
	s_or_b64 exec, exec, s[0:1]
	s_waitcnt vmcnt(14)
	v_lshlrev_b32_e32 v34, 16, v108
	v_and_b32_e32 v35, 0xffff0000, v108
	v_lshlrev_b32_e32 v36, 16, v109
	v_and_b32_e32 v37, 0xffff0000, v109
	v_lshlrev_b32_e32 v38, 16, v110
	v_and_b32_e32 v39, 0xffff0000, v110
	v_lshlrev_b32_e32 v40, 16, v111
	v_and_b32_e32 v41, 0xffff0000, v111
	v_pk_add_f32 v[30:31], v[30:31], v[36:37]
	v_pk_add_f32 v[28:29], v[28:29], v[34:35]
	v_pk_add_f32 v[34:35], v[26:27], v[40:41]
	v_pk_add_f32 v[26:27], v[24:25], v[38:39]
	v_mul_f32_e32 v24, v29, v29
	v_mul_f32_e32 v25, v31, v31
	v_fmac_f32_e32 v24, v28, v28
	v_fmac_f32_e32 v25, v30, v30
	v_add_f32_e32 v24, v24, v25
	v_mul_f32_e32 v25, v27, v27
	v_mul_f32_e32 v36, v35, v35
	v_fmac_f32_e32 v25, v26, v26
	v_fmac_f32_e32 v36, v34, v34
	s_waitcnt vmcnt(14)
	v_lshlrev_b32_e32 v42, 16, v104
	v_and_b32_e32 v43, 0xffff0000, v104
	v_lshlrev_b32_e32 v44, 16, v105
	v_and_b32_e32 v45, 0xffff0000, v105
	v_add_f32_e32 v25, v25, v36
	v_lshlrev_b32_e32 v48, 16, v107
	v_and_b32_e32 v49, 0xffff0000, v107
	v_add_f32_e32 v36, v24, v25
	v_cvt_pk_bf16_f32 v24, v28, v29
	v_cvt_pk_bf16_f32 v25, v30, v31
	v_pk_add_f32 v[22:23], v[22:23], v[44:45]
	v_pk_add_f32 v[20:21], v[20:21], v[42:43]
	v_lshlrev_b32_e32 v46, 16, v106
	v_and_b32_e32 v47, 0xffff0000, v106
	v_cvt_pk_bf16_f32 v26, v26, v27
	v_cvt_pk_bf16_f32 v27, v34, v35
	global_store_dwordx4 v[118:119], v[24:27], off sc1
	s_nop 1
	v_pk_add_f32 v[24:25], v[18:19], v[48:49]
	v_mul_f32_e32 v18, v21, v21
	v_mul_f32_e32 v19, v23, v23
	v_pk_add_f32 v[16:17], v[16:17], v[46:47]
	v_fmac_f32_e32 v18, v20, v20
	v_fmac_f32_e32 v19, v22, v22
	v_add_f32_e32 v18, v18, v19
	v_mul_f32_e32 v19, v17, v17
	v_mul_f32_e32 v26, v25, v25
	v_fmac_f32_e32 v19, v16, v16
	v_fmac_f32_e32 v26, v24, v24
	v_add_f32_e32 v19, v19, v26
	v_add_f32_e32 v18, v18, v19
	v_add_f32_e32 v26, v36, v18
	ds_bpermute_b32 v27, v120, v26
	v_cvt_pk_bf16_f32 v18, v20, v21
	v_cvt_pk_bf16_f32 v20, v16, v17
	s_waitcnt lgkmcnt(1)
	v_lshl_add_u64 v[32:33], v[118:119], 0, s[14:15]
	v_cvt_pk_bf16_f32 v19, v22, v23
	s_waitcnt lgkmcnt(0)
	v_add_f32_e32 v16, v26, v27
	ds_bpermute_b32 v17, v121, v16
	v_cvt_pk_bf16_f32 v21, v24, v25
	global_store_dwordx4 v[32:33], v[18:21], off sc1
	s_nop 1
	s_and_saveexec_b64 s[0:1], s[6:7]
	s_cbranch_execz .LBB0_1111
	s_waitcnt lgkmcnt(0)
	v_add_f32_e32 v18, v16, v17
	s_lshl_b32 s24, s47, 2
	v_lshlrev_b64 v[16:17], 6, v[116:117]
	s_ashr_i32 s25, s24, 31
	v_lshl_add_u64 v[16:17], s[16:17], 0, v[16:17]
	v_lshl_add_u64 v[16:17], s[24:25], 2, v[16:17]
	s_lshl_b32 s4, s41, 2
	v_lshl_add_u64 v[16:17], v[16:17], 0, s[4:5]
	global_store_dword v[16:17], v18, off sc1
.LBB0_1111:
	s_or_b64 exec, exec, s[0:1]
	s_waitcnt vmcnt(15)
	v_lshlrev_b32_e32 v18, 16, v100
	v_and_b32_e32 v19, 0xffff0000, v100
	v_lshlrev_b32_e32 v20, 16, v101
	v_and_b32_e32 v21, 0xffff0000, v101
	v_lshlrev_b32_e32 v22, 16, v102
	v_and_b32_e32 v23, 0xffff0000, v102
	v_lshlrev_b32_e32 v24, 16, v103
	v_and_b32_e32 v25, 0xffff0000, v103
	v_pk_add_f32 v[14:15], v[14:15], v[20:21]
	v_pk_add_f32 v[12:13], v[12:13], v[18:19]
	v_pk_add_f32 v[18:19], v[10:11], v[24:25]
	v_pk_add_f32 v[10:11], v[8:9], v[22:23]
	v_mul_f32_e32 v8, v13, v13
	v_mul_f32_e32 v9, v15, v15
	v_fmac_f32_e32 v8, v12, v12
	v_fmac_f32_e32 v9, v14, v14
	v_add_f32_e32 v8, v8, v9
	v_mul_f32_e32 v9, v11, v11
	v_mul_f32_e32 v20, v19, v19
	v_fmac_f32_e32 v9, v10, v10
	v_fmac_f32_e32 v20, v18, v18
	s_waitcnt vmcnt(15)
	v_lshlrev_b32_e32 v26, 16, v96
	v_and_b32_e32 v27, 0xffff0000, v96
	v_lshlrev_b32_e32 v28, 16, v97
	v_and_b32_e32 v29, 0xffff0000, v97
	v_add_f32_e32 v9, v9, v20
	v_lshlrev_b32_e32 v32, 16, v99
	v_and_b32_e32 v33, 0xffff0000, v99
	v_add_f32_e32 v20, v8, v9
	v_cvt_pk_bf16_f32 v8, v12, v13
	v_cvt_pk_bf16_f32 v9, v14, v15
	v_pk_add_f32 v[6:7], v[6:7], v[28:29]
	v_pk_add_f32 v[4:5], v[4:5], v[26:27]
	v_lshlrev_b32_e32 v30, 16, v98
	v_and_b32_e32 v31, 0xffff0000, v98
	v_cvt_pk_bf16_f32 v10, v10, v11
	v_cvt_pk_bf16_f32 v11, v18, v19
	global_store_dwordx4 v[114:115], v[8:11], off sc1
	s_nop 1
	v_pk_add_f32 v[8:9], v[2:3], v[32:33]
	v_mul_f32_e32 v2, v5, v5
	v_mul_f32_e32 v3, v7, v7
	v_pk_add_f32 v[0:1], v[0:1], v[30:31]
	v_fmac_f32_e32 v2, v4, v4
	v_fmac_f32_e32 v3, v6, v6
	v_add_f32_e32 v2, v2, v3
	v_mul_f32_e32 v3, v1, v1
	v_mul_f32_e32 v10, v9, v9
	v_fmac_f32_e32 v3, v0, v0
	v_fmac_f32_e32 v10, v8, v8
	v_add_f32_e32 v3, v3, v10
	v_add_f32_e32 v2, v2, v3
	v_add_f32_e32 v10, v20, v2
	ds_bpermute_b32 v11, v120, v10
	v_cvt_pk_bf16_f32 v2, v4, v5
	v_cvt_pk_bf16_f32 v4, v0, v1
	s_waitcnt lgkmcnt(1)
	v_lshl_add_u64 v[16:17], v[114:115], 0, s[14:15]
	v_cvt_pk_bf16_f32 v3, v6, v7
	s_waitcnt lgkmcnt(0)
	v_add_f32_e32 v0, v10, v11
	ds_bpermute_b32 v1, v121, v0
	v_cvt_pk_bf16_f32 v5, v8, v9
	global_store_dwordx4 v[16:17], v[2:5], off sc1
	s_nop 1
	s_and_saveexec_b64 s[0:1], s[6:7]
	s_cbranch_execz .LBB0_1113
	s_waitcnt lgkmcnt(0)
	v_add_f32_e32 v2, v0, v1
	s_lshl_b32 s24, s47, 2
	v_lshlrev_b64 v[0:1], 6, v[112:113]
	s_ashr_i32 s25, s24, 31
	v_lshl_add_u64 v[0:1], s[16:17], 0, v[0:1]
	v_lshl_add_u64 v[0:1], s[24:25], 2, v[0:1]
	s_lshl_b32 s4, s41, 2
	v_lshl_add_u64 v[0:1], v[0:1], 0, s[4:5]
	global_store_dword v[0:1], v2, off sc1

.LBB0_2667:
	v_lshl_add_u32 v202, s24, 8, v171
	v_lshl_or_b32 v128, s45, 8, v213
	v_ashrrev_i32_e32 v203, 31, v202
	v_lshlrev_b64 v[130:131], 11, v[202:203]
	v_ashrrev_i32_e32 v129, 31, v128
	v_lshl_add_u64 v[130:131], s[12:13], 0, v[130:131]
	v_lshlrev_b64 v[204:205], 1, v[128:129]
	v_lshl_add_u64 v[226:227], v[130:131], 0, v[204:205]
	global_load_dwordx4 v[218:221], v[226:227], off
	global_load_dwordx4 v[222:225], v[226:227], off offset:256
	v_or_b32_e32 v208, 16, v202
	v_or_b32_e32 v200, 32, v202
	v_or_b32_e32 v196, 48, v202
	v_add_u32_e32 v192, 0x80, v202
	v_add_u32_e32 v188, 0x90, v202
	v_ashrrev_i32_e32 v209, 31, v208
	v_ashrrev_i32_e32 v201, 31, v200
	v_ashrrev_i32_e32 v197, 31, v196
	v_ashrrev_i32_e32 v193, 31, v192
	v_ashrrev_i32_e32 v189, 31, v188
	v_lshlrev_b64 v[128:129], 11, v[208:209]
	v_lshlrev_b64 v[130:131], 11, v[200:201]
	v_lshlrev_b64 v[132:133], 11, v[196:197]
	v_lshlrev_b64 v[134:135], 11, v[192:193]
	v_lshlrev_b64 v[136:137], 11, v[188:189]
	v_lshl_add_u64 v[128:129], s[12:13], 0, v[128:129]
	v_lshl_add_u64 v[130:131], s[12:13], 0, v[130:131]
	v_lshl_add_u64 v[132:133], s[12:13], 0, v[132:133]
	v_lshl_add_u64 v[134:135], s[12:13], 0, v[134:135]
	v_lshl_add_u64 v[136:137], s[12:13], 0, v[136:137]
	v_lshl_add_u64 v[210:211], v[128:129], 0, v[204:205]
	v_lshl_add_u64 v[206:207], v[130:131], 0, v[204:205]
	v_lshl_add_u64 v[198:199], v[132:133], 0, v[204:205]
	v_lshl_add_u64 v[194:195], v[134:135], 0, v[204:205]
	v_lshl_add_u64 v[190:191], v[136:137], 0, v[204:205]
	global_load_dwordx4 v[164:167], v[210:211], off
	global_load_dwordx4 v[160:163], v[210:211], off offset:256
	global_load_dwordx4 v[156:159], v[206:207], off
	global_load_dwordx4 v[152:155], v[206:207], off offset:256
	global_load_dwordx4 v[148:151], v[198:199], off
	global_load_dwordx4 v[144:147], v[198:199], off offset:256
	global_load_dwordx4 v[140:143], v[194:195], off
	global_load_dwordx4 v[136:139], v[194:195], off offset:256
	global_load_dwordx4 v[132:135], v[190:191], off
	global_load_dwordx4 v[128:131], v[190:191], off offset:256
	v_lshl_add_u64 v[228:229], v[226:227], 0, s[14:15]
	s_waitcnt vmcnt(8)
	v_lshlrev_b32_e32 v230, 16, v218
	v_and_b32_e32 v231, 0xffff0000, v218
	v_lshlrev_b32_e32 v218, 16, v219
	v_and_b32_e32 v219, 0xffff0000, v219
	v_lshlrev_b32_e32 v232, 16, v220
	v_and_b32_e32 v233, 0xffff0000, v220
	v_lshlrev_b32_e32 v220, 16, v221
	v_and_b32_e32 v221, 0xffff0000, v221
	v_lshlrev_b32_e32 v234, 16, v222
	v_and_b32_e32 v235, 0xffff0000, v222
	v_lshlrev_b32_e32 v222, 16, v223
	v_and_b32_e32 v223, 0xffff0000, v223
	v_lshlrev_b32_e32 v236, 16, v224
	v_and_b32_e32 v237, 0xffff0000, v224
	v_lshlrev_b32_e32 v224, 16, v225
	v_and_b32_e32 v225, 0xffff0000, v225
	v_pk_add_f32 v[126:127], v[126:127], v[218:219]
	v_pk_add_f32 v[124:125], v[124:125], v[230:231]
	v_pk_add_f32 v[122:123], v[122:123], v[220:221]
	v_pk_add_f32 v[120:121], v[120:121], v[232:233]
	v_pk_add_f32 v[118:119], v[118:119], v[222:223]
	v_pk_add_f32 v[218:219], v[114:115], v[224:225]
	v_mul_f32_e32 v222, v125, v125
	v_mul_f32_e32 v223, v127, v127
	v_mul_f32_e32 v224, v121, v121
	v_mul_f32_e32 v225, v123, v123
	v_pk_add_f32 v[220:221], v[112:113], v[236:237]
	v_cvt_pk_bf16_f32 v112, v124, v125
	v_cvt_pk_bf16_f32 v113, v126, v127
	v_fmac_f32_e32 v222, v124, v124
	v_fmac_f32_e32 v223, v126, v126
	v_fmac_f32_e32 v224, v120, v120
	v_fmac_f32_e32 v225, v122, v122
	v_pk_add_f32 v[116:117], v[116:117], v[234:235]
	v_cvt_pk_bf16_f32 v114, v120, v121
	v_cvt_pk_bf16_f32 v115, v122, v123
	global_store_dwordx4 v[226:227], v[112:115], off sc1
	s_nop 1
	v_add_f32_e32 v112, v222, v223
	v_add_f32_e32 v113, v224, v225
	v_mul_f32_e32 v121, v117, v117
	v_mul_f32_e32 v123, v119, v119
	v_add_f32_e32 v112, v112, v113
	v_mul_f32_e32 v113, v221, v221
	v_mul_f32_e32 v115, v219, v219
	v_fmac_f32_e32 v121, v116, v116
	v_fmac_f32_e32 v123, v118, v118
	v_fmac_f32_e32 v113, v220, v220
	v_fmac_f32_e32 v115, v218, v218
	v_add_f32_e32 v114, v121, v123
	v_add_f32_e32 v113, v113, v115
	v_add_f32_e32 v113, v114, v113
	v_and_b32_e32 v114, 64, v217
	v_add_f32_e32 v112, v112, v113
	v_xor_b32_e32 v113, 16, v217
	v_add_u32_e32 v121, 64, v114
	v_cmp_lt_i32_e32 vcc, v113, v121
	v_cvt_pk_bf16_f32 v114, v116, v117
	v_cvt_pk_bf16_f32 v115, v118, v119
	v_cndmask_b32_e32 v113, v217, v113, vcc
	v_lshlrev_b32_e32 v120, 2, v113
	ds_bpermute_b32 v113, v120, v112
	v_cvt_pk_bf16_f32 v116, v220, v221
	v_cvt_pk_bf16_f32 v117, v218, v219
	global_store_dwordx4 v[228:229], v[114:117], off sc1
	s_nop 1
	s_waitcnt lgkmcnt(0)
	v_add_f32_e32 v112, v112, v113
	v_xor_b32_e32 v113, 32, v217
	v_cmp_lt_i32_e32 vcc, v113, v121
	s_nop 1
	v_cndmask_b32_e32 v113, v217, v113, vcc
	v_lshlrev_b32_e32 v121, 2, v113
	ds_bpermute_b32 v113, v121, v112
	s_and_saveexec_b64 s[0:1], s[6:7]
	s_cbranch_execz .LBB0_2669
	s_waitcnt lgkmcnt(0)
	v_add_f32_e32 v114, v112, v113
	s_lshl_b32 s24, s45, 2
	v_lshlrev_b64 v[112:113], 6, v[202:203]
	s_ashr_i32 s25, s24, 31
	v_lshl_add_u64 v[112:113], s[16:17], 0, v[112:113]
	v_lshl_add_u64 v[112:113], s[24:25], 2, v[112:113]
	s_lshl_b32 s4, s40, 2
	v_lshl_add_u64 v[112:113], v[112:113], 0, s[4:5]
	global_store_dword v[112:113], v114, off sc1
.LBB0_2669:
	s_or_b64 exec, exec, s[0:1]
	v_lshlrev_b32_e32 v114, 16, v164
	v_and_b32_e32 v115, 0xffff0000, v164
	v_lshlrev_b32_e32 v116, 16, v165
	v_and_b32_e32 v117, 0xffff0000, v165
	v_lshlrev_b32_e32 v118, 16, v166
	v_and_b32_e32 v119, 0xffff0000, v166
	v_lshlrev_b32_e32 v122, 16, v167
	v_and_b32_e32 v123, 0xffff0000, v167
	v_pk_add_f32 v[110:111], v[110:111], v[116:117]
	v_pk_add_f32 v[108:109], v[108:109], v[114:115]
	v_pk_add_f32 v[114:115], v[106:107], v[122:123]
	v_pk_add_f32 v[106:107], v[104:105], v[118:119]
	v_mul_f32_e32 v104, v109, v109
	v_mul_f32_e32 v105, v111, v111
	v_fmac_f32_e32 v104, v108, v108
	v_fmac_f32_e32 v105, v110, v110
	v_add_f32_e32 v104, v104, v105
	v_mul_f32_e32 v105, v107, v107
	v_mul_f32_e32 v116, v115, v115
	v_fmac_f32_e32 v105, v106, v106
	v_fmac_f32_e32 v116, v114, v114
	v_lshlrev_b32_e32 v124, 16, v160
	v_and_b32_e32 v125, 0xffff0000, v160
	v_lshlrev_b32_e32 v126, 16, v161
	v_and_b32_e32 v127, 0xffff0000, v161
	v_add_f32_e32 v105, v105, v116
	v_lshlrev_b32_e32 v160, 16, v162
	v_and_b32_e32 v161, 0xffff0000, v162
	v_lshlrev_b32_e32 v162, 16, v163
	v_and_b32_e32 v163, 0xffff0000, v163
	v_add_f32_e32 v116, v104, v105
	v_cvt_pk_bf16_f32 v104, v108, v109
	v_cvt_pk_bf16_f32 v105, v110, v111
	v_pk_add_f32 v[102:103], v[102:103], v[126:127]
	v_pk_add_f32 v[100:101], v[100:101], v[124:125]
	v_cvt_pk_bf16_f32 v106, v106, v107
	v_cvt_pk_bf16_f32 v107, v114, v115
	global_store_dwordx4 v[210:211], v[104:107], off sc1
	s_nop 1
	v_pk_add_f32 v[104:105], v[98:99], v[162:163]
	v_mul_f32_e32 v98, v101, v101
	v_mul_f32_e32 v99, v103, v103
	v_pk_add_f32 v[96:97], v[96:97], v[160:161]
	v_fmac_f32_e32 v98, v100, v100
	v_fmac_f32_e32 v99, v102, v102
	v_add_f32_e32 v98, v98, v99
	v_mul_f32_e32 v99, v97, v97
	v_mul_f32_e32 v106, v105, v105
	v_fmac_f32_e32 v99, v96, v96
	v_fmac_f32_e32 v106, v104, v104
	v_add_f32_e32 v99, v99, v106
	v_add_f32_e32 v98, v98, v99
	v_add_f32_e32 v106, v116, v98
	ds_bpermute_b32 v107, v120, v106
	v_cvt_pk_bf16_f32 v98, v100, v101
	v_cvt_pk_bf16_f32 v100, v96, v97
	s_waitcnt lgkmcnt(1)
	v_lshl_add_u64 v[112:113], v[210:211], 0, s[14:15]
	v_cvt_pk_bf16_f32 v99, v102, v103
	s_waitcnt lgkmcnt(0)
	v_add_f32_e32 v96, v106, v107
	ds_bpermute_b32 v97, v121, v96
	v_cvt_pk_bf16_f32 v101, v104, v105
	global_store_dwordx4 v[112:113], v[98:101], off sc1
	s_nop 1
	s_and_saveexec_b64 s[0:1], s[6:7]
	s_cbranch_execz .LBB0_2671
	s_waitcnt lgkmcnt(0)
	v_add_f32_e32 v98, v96, v97
	s_lshl_b32 s24, s45, 2
	v_lshlrev_b64 v[96:97], 6, v[208:209]
	s_ashr_i32 s25, s24, 31
	v_lshl_add_u64 v[96:97], s[16:17], 0, v[96:97]
	v_lshl_add_u64 v[96:97], s[24:25], 2, v[96:97]
	s_lshl_b32 s4, s40, 2
	v_lshl_add_u64 v[96:97], v[96:97], 0, s[4:5]
	global_store_dword v[96:97], v98, off sc1
.LBB0_2671:
	s_or_b64 exec, exec, s[0:1]
	v_add_u32_e32 v116, 0xa0, v202
	v_ashrrev_i32_e32 v117, 31, v116
	s_waitcnt lgkmcnt(0)
	v_lshlrev_b64 v[96:97], 11, v[116:117]
	v_add_u32_e32 v112, 0xb0, v202
	v_lshl_add_u64 v[96:97], s[12:13], 0, v[96:97]
	v_ashrrev_i32_e32 v113, 31, v112
	v_lshl_add_u64 v[118:119], v[96:97], 0, v[204:205]
	v_lshlrev_b64 v[96:97], 11, v[112:113]
	v_lshl_add_u64 v[96:97], s[12:13], 0, v[96:97]
	v_lshl_add_u64 v[114:115], v[96:97], 0, v[204:205]
	global_load_dwordx4 v[108:111], v[118:119], off
	global_load_dwordx4 v[104:107], v[118:119], off offset:256
	global_load_dwordx4 v[100:103], v[114:115], off
	global_load_dwordx4 v[96:99], v[114:115], off offset:256
	s_waitcnt vmcnt(14)
	v_lshlrev_b32_e32 v124, 16, v156
	v_and_b32_e32 v125, 0xffff0000, v156
	v_lshlrev_b32_e32 v126, 16, v157
	v_and_b32_e32 v127, 0xffff0000, v157
	v_lshlrev_b32_e32 v156, 16, v158
	v_and_b32_e32 v157, 0xffff0000, v158
	v_lshlrev_b32_e32 v158, 16, v159
	v_and_b32_e32 v159, 0xffff0000, v159
	v_pk_add_f32 v[94:95], v[94:95], v[126:127]
	v_pk_add_f32 v[92:93], v[92:93], v[124:125]
	v_pk_add_f32 v[124:125], v[90:91], v[158:159]
	v_pk_add_f32 v[90:91], v[88:89], v[156:157]
	v_mul_f32_e32 v88, v93, v93
	v_mul_f32_e32 v89, v95, v95
	v_fmac_f32_e32 v88, v92, v92
	v_fmac_f32_e32 v89, v94, v94
	v_add_f32_e32 v88, v88, v89
	v_mul_f32_e32 v89, v91, v91
	v_mul_f32_e32 v126, v125, v125
	v_fmac_f32_e32 v89, v90, v90
	v_fmac_f32_e32 v126, v124, v124
	v_lshlrev_b32_e32 v160, 16, v152
	v_and_b32_e32 v161, 0xffff0000, v152
	v_lshlrev_b32_e32 v152, 16, v153
	v_and_b32_e32 v153, 0xffff0000, v153
	v_add_f32_e32 v89, v89, v126
	v_lshlrev_b32_e32 v162, 16, v154
	v_and_b32_e32 v163, 0xffff0000, v154
	v_lshlrev_b32_e32 v154, 16, v155
	v_and_b32_e32 v155, 0xffff0000, v155
	v_add_f32_e32 v126, v88, v89
	v_cvt_pk_bf16_f32 v88, v92, v93
	v_cvt_pk_bf16_f32 v89, v94, v95
	v_pk_add_f32 v[86:87], v[86:87], v[152:153]
	v_pk_add_f32 v[84:85], v[84:85], v[160:161]
	v_cvt_pk_bf16_f32 v90, v90, v91
	v_cvt_pk_bf16_f32 v91, v124, v125
	global_store_dwordx4 v[206:207], v[88:91], off sc1
	s_nop 1
	v_pk_add_f32 v[88:89], v[82:83], v[154:155]
	v_mul_f32_e32 v82, v85, v85
	v_mul_f32_e32 v83, v87, v87
	v_pk_add_f32 v[80:81], v[80:81], v[162:163]
	v_fmac_f32_e32 v82, v84, v84
	v_fmac_f32_e32 v83, v86, v86
	v_add_f32_e32 v82, v82, v83
	v_mul_f32_e32 v83, v81, v81
	v_mul_f32_e32 v90, v89, v89
	v_fmac_f32_e32 v83, v80, v80
	v_fmac_f32_e32 v90, v88, v88
	v_add_f32_e32 v83, v83, v90
	v_add_f32_e32 v82, v82, v83
	v_add_f32_e32 v90, v126, v82
	ds_bpermute_b32 v91, v120, v90
	v_cvt_pk_bf16_f32 v82, v84, v85
	v_cvt_pk_bf16_f32 v84, v80, v81
	v_lshl_add_u64 v[122:123], v[206:207], 0, s[14:15]
	v_cvt_pk_bf16_f32 v83, v86, v87
	s_waitcnt lgkmcnt(0)
	v_add_f32_e32 v80, v90, v91
	ds_bpermute_b32 v81, v121, v80
	v_cvt_pk_bf16_f32 v85, v88, v89
	global_store_dwordx4 v[122:123], v[82:85], off sc1
	s_nop 1
	s_and_saveexec_b64 s[0:1], s[6:7]
	s_cbranch_execz .LBB0_2673
	s_waitcnt lgkmcnt(0)
	v_add_f32_e32 v82, v80, v81
	s_lshl_b32 s24, s45, 2
	v_lshlrev_b64 v[80:81], 6, v[200:201]
	s_ashr_i32 s25, s24, 31
	v_lshl_add_u64 v[80:81], s[16:17], 0, v[80:81]
	v_lshl_add_u64 v[80:81], s[24:25], 2, v[80:81]
	s_lshl_b32 s4, s40, 2
	v_lshl_add_u64 v[80:81], v[80:81], 0, s[4:5]
	global_store_dword v[80:81], v82, off sc1
.LBB0_2673:
	s_or_b64 exec, exec, s[0:1]
	v_lshlrev_b32_e32 v82, 16, v148
	v_and_b32_e32 v83, 0xffff0000, v148
	v_lshlrev_b32_e32 v84, 16, v149
	v_and_b32_e32 v85, 0xffff0000, v149
	v_lshlrev_b32_e32 v86, 16, v150
	v_and_b32_e32 v87, 0xffff0000, v150
	v_lshlrev_b32_e32 v88, 16, v151
	v_and_b32_e32 v89, 0xffff0000, v151
	v_pk_add_f32 v[78:79], v[78:79], v[84:85]
	v_pk_add_f32 v[76:77], v[76:77], v[82:83]
	v_pk_add_f32 v[82:83], v[74:75], v[88:89]
	v_pk_add_f32 v[74:75], v[72:73], v[86:87]
	v_mul_f32_e32 v72, v77, v77
	v_mul_f32_e32 v73, v79, v79
	v_fmac_f32_e32 v72, v76, v76
	v_fmac_f32_e32 v73, v78, v78
	v_add_f32_e32 v72, v72, v73
	v_mul_f32_e32 v73, v75, v75
	v_mul_f32_e32 v84, v83, v83
	v_fmac_f32_e32 v73, v74, v74
	v_fmac_f32_e32 v84, v82, v82
	v_lshlrev_b32_e32 v90, 16, v144
	v_and_b32_e32 v91, 0xffff0000, v144
	v_lshlrev_b32_e32 v92, 16, v145
	v_and_b32_e32 v93, 0xffff0000, v145
	v_add_f32_e32 v73, v73, v84
	v_lshlrev_b32_e32 v122, 16, v147
	v_and_b32_e32 v123, 0xffff0000, v147
	v_add_f32_e32 v84, v72, v73
	v_cvt_pk_bf16_f32 v72, v76, v77
	v_cvt_pk_bf16_f32 v73, v78, v79
	v_pk_add_f32 v[70:71], v[70:71], v[92:93]
	v_pk_add_f32 v[68:69], v[68:69], v[90:91]
	v_lshlrev_b32_e32 v94, 16, v146
	v_and_b32_e32 v95, 0xffff0000, v146
	v_cvt_pk_bf16_f32 v74, v74, v75
	v_cvt_pk_bf16_f32 v75, v82, v83
	global_store_dwordx4 v[198:199], v[72:75], off sc1
	s_nop 1
	v_pk_add_f32 v[72:73], v[66:67], v[122:123]
	v_mul_f32_e32 v66, v69, v69
	v_mul_f32_e32 v67, v71, v71
	v_pk_add_f32 v[64:65], v[64:65], v[94:95]
	v_fmac_f32_e32 v66, v68, v68
	v_fmac_f32_e32 v67, v70, v70
	v_add_f32_e32 v66, v66, v67
	v_mul_f32_e32 v67, v65, v65
	v_mul_f32_e32 v74, v73, v73
	v_fmac_f32_e32 v67, v64, v64
	v_fmac_f32_e32 v74, v72, v72
	v_add_f32_e32 v67, v67, v74
	v_add_f32_e32 v66, v66, v67
	v_add_f32_e32 v74, v84, v66
	ds_bpermute_b32 v75, v120, v74
	v_cvt_pk_bf16_f32 v66, v68, v69
	v_cvt_pk_bf16_f32 v68, v64, v65
	s_waitcnt lgkmcnt(1)
	v_lshl_add_u64 v[80:81], v[198:199], 0, s[14:15]
	v_cvt_pk_bf16_f32 v67, v70, v71
	s_waitcnt lgkmcnt(0)
	v_add_f32_e32 v64, v74, v75
	ds_bpermute_b32 v65, v121, v64
	v_cvt_pk_bf16_f32 v69, v72, v73
	global_store_dwordx4 v[80:81], v[66:69], off sc1
	s_nop 1
	s_and_saveexec_b64 s[0:1], s[6:7]
	s_cbranch_execz .LBB0_2675
	s_waitcnt lgkmcnt(0)
	v_add_f32_e32 v66, v64, v65
	s_lshl_b32 s24, s45, 2
	v_lshlrev_b64 v[64:65], 6, v[196:197]
	s_ashr_i32 s25, s24, 31
	v_lshl_add_u64 v[64:65], s[16:17], 0, v[64:65]
	v_lshl_add_u64 v[64:65], s[24:25], 2, v[64:65]
	s_lshl_b32 s4, s40, 2
	v_lshl_add_u64 v[64:65], v[64:65], 0, s[4:5]
	global_store_dword v[64:65], v66, off sc1
.LBB0_2675:
	s_or_b64 exec, exec, s[0:1]
	s_waitcnt vmcnt(16)
	v_lshlrev_b32_e32 v66, 16, v140
	v_and_b32_e32 v67, 0xffff0000, v140
	v_lshlrev_b32_e32 v68, 16, v141
	v_and_b32_e32 v69, 0xffff0000, v141
	v_lshlrev_b32_e32 v70, 16, v142
	v_and_b32_e32 v71, 0xffff0000, v142
	v_lshlrev_b32_e32 v72, 16, v143
	v_and_b32_e32 v73, 0xffff0000, v143
	v_pk_add_f32 v[62:63], v[62:63], v[68:69]
	v_pk_add_f32 v[60:61], v[60:61], v[66:67]
	v_pk_add_f32 v[66:67], v[58:59], v[72:73]
	v_pk_add_f32 v[58:59], v[56:57], v[70:71]
	v_mul_f32_e32 v56, v61, v61
	v_mul_f32_e32 v57, v63, v63
	v_fmac_f32_e32 v56, v60, v60
	v_fmac_f32_e32 v57, v62, v62
	v_add_f32_e32 v56, v56, v57
	v_mul_f32_e32 v57, v59, v59
	v_mul_f32_e32 v68, v67, v67
	v_fmac_f32_e32 v57, v58, v58
	v_fmac_f32_e32 v68, v66, v66
	v_lshlrev_b32_e32 v74, 16, v136
	v_and_b32_e32 v75, 0xffff0000, v136
	v_lshlrev_b32_e32 v76, 16, v137
	v_and_b32_e32 v77, 0xffff0000, v137
	v_add_f32_e32 v57, v57, v68
	v_lshlrev_b32_e32 v80, 16, v139
	v_and_b32_e32 v81, 0xffff0000, v139
	v_add_f32_e32 v68, v56, v57
	v_cvt_pk_bf16_f32 v56, v60, v61
	v_cvt_pk_bf16_f32 v57, v62, v63
	v_pk_add_f32 v[54:55], v[54:55], v[76:77]
	v_pk_add_f32 v[52:53], v[52:53], v[74:75]
	v_lshlrev_b32_e32 v78, 16, v138
	v_and_b32_e32 v79, 0xffff0000, v138
	v_cvt_pk_bf16_f32 v58, v58, v59
	v_cvt_pk_bf16_f32 v59, v66, v67
	global_store_dwordx4 v[194:195], v[56:59], off sc1
	s_nop 1
	v_pk_add_f32 v[56:57], v[50:51], v[80:81]
	v_mul_f32_e32 v50, v53, v53
	v_mul_f32_e32 v51, v55, v55
	v_pk_add_f32 v[48:49], v[48:49], v[78:79]
	v_fmac_f32_e32 v50, v52, v52
	v_fmac_f32_e32 v51, v54, v54
	v_add_f32_e32 v50, v50, v51
	v_mul_f32_e32 v51, v49, v49
	v_mul_f32_e32 v58, v57, v57
	v_fmac_f32_e32 v51, v48, v48
	v_fmac_f32_e32 v58, v56, v56
	v_add_f32_e32 v51, v51, v58
	v_add_f32_e32 v50, v50, v51
	v_add_f32_e32 v58, v68, v50
	ds_bpermute_b32 v59, v120, v58
	v_cvt_pk_bf16_f32 v50, v52, v53
	v_cvt_pk_bf16_f32 v52, v48, v49
	s_waitcnt lgkmcnt(1)
	v_lshl_add_u64 v[64:65], v[194:195], 0, s[14:15]
	v_cvt_pk_bf16_f32 v51, v54, v55
	s_waitcnt lgkmcnt(0)
	v_add_f32_e32 v48, v58, v59
	ds_bpermute_b32 v49, v121, v48
	v_cvt_pk_bf16_f32 v53, v56, v57
	global_store_dwordx4 v[64:65], v[50:53], off sc1
	s_nop 1
	s_and_saveexec_b64 s[0:1], s[6:7]
	s_cbranch_execz .LBB0_2677
	s_waitcnt lgkmcnt(0)
	v_add_f32_e32 v50, v48, v49
	s_lshl_b32 s24, s45, 2
	v_lshlrev_b64 v[48:49], 6, v[192:193]
	s_ashr_i32 s25, s24, 31
	v_lshl_add_u64 v[48:49], s[16:17], 0, v[48:49]
	v_lshl_add_u64 v[48:49], s[24:25], 2, v[48:49]
	s_lshl_b32 s4, s40, 2
	v_lshl_add_u64 v[48:49], v[48:49], 0, s[4:5]
	global_store_dword v[48:49], v50, off sc1
.LBB0_2677:
	s_or_b64 exec, exec, s[0:1]
	v_lshlrev_b32_e32 v50, 16, v132
	v_and_b32_e32 v51, 0xffff0000, v132
	v_lshlrev_b32_e32 v52, 16, v133
	v_and_b32_e32 v53, 0xffff0000, v133
	v_lshlrev_b32_e32 v54, 16, v134
	v_and_b32_e32 v55, 0xffff0000, v134
	v_lshlrev_b32_e32 v56, 16, v135
	v_and_b32_e32 v57, 0xffff0000, v135
	v_pk_add_f32 v[46:47], v[46:47], v[52:53]
	v_pk_add_f32 v[44:45], v[44:45], v[50:51]
	v_pk_add_f32 v[50:51], v[42:43], v[56:57]
	v_pk_add_f32 v[42:43], v[40:41], v[54:55]
	v_mul_f32_e32 v40, v45, v45
	v_mul_f32_e32 v41, v47, v47
	v_fmac_f32_e32 v40, v44, v44
	v_fmac_f32_e32 v41, v46, v46
	v_add_f32_e32 v40, v40, v41
	v_mul_f32_e32 v41, v43, v43
	v_mul_f32_e32 v52, v51, v51
	v_fmac_f32_e32 v41, v42, v42
	v_fmac_f32_e32 v52, v50, v50
	v_lshlrev_b32_e32 v58, 16, v128
	v_and_b32_e32 v59, 0xffff0000, v128
	v_lshlrev_b32_e32 v60, 16, v129
	v_and_b32_e32 v61, 0xffff0000, v129
	v_add_f32_e32 v41, v41, v52
	v_lshlrev_b32_e32 v64, 16, v131
	v_and_b32_e32 v65, 0xffff0000, v131
	v_add_f32_e32 v52, v40, v41
	v_cvt_pk_bf16_f32 v40, v44, v45
	v_cvt_pk_bf16_f32 v41, v46, v47
	v_pk_add_f32 v[38:39], v[38:39], v[60:61]
	v_pk_add_f32 v[36:37], v[36:37], v[58:59]
	v_lshlrev_b32_e32 v62, 16, v130
	v_and_b32_e32 v63, 0xffff0000, v130
	v_cvt_pk_bf16_f32 v42, v42, v43
	v_cvt_pk_bf16_f32 v43, v50, v51
	global_store_dwordx4 v[190:191], v[40:43], off sc1
	s_nop 1
	v_pk_add_f32 v[40:41], v[34:35], v[64:65]
	v_mul_f32_e32 v34, v37, v37
	v_mul_f32_e32 v35, v39, v39
	v_pk_add_f32 v[32:33], v[32:33], v[62:63]
	v_fmac_f32_e32 v34, v36, v36
	v_fmac_f32_e32 v35, v38, v38
	v_add_f32_e32 v34, v34, v35
	v_mul_f32_e32 v35, v33, v33
	v_mul_f32_e32 v42, v41, v41
	v_fmac_f32_e32 v35, v32, v32
	v_fmac_f32_e32 v42, v40, v40
	v_add_f32_e32 v35, v35, v42
	v_add_f32_e32 v34, v34, v35
	v_add_f32_e32 v42, v52, v34
	ds_bpermute_b32 v43, v120, v42
	v_cvt_pk_bf16_f32 v34, v36, v37
	v_cvt_pk_bf16_f32 v36, v32, v33
	s_waitcnt lgkmcnt(1)
	v_lshl_add_u64 v[48:49], v[190:191], 0, s[14:15]
	v_cvt_pk_bf16_f32 v35, v38, v39
	s_waitcnt lgkmcnt(0)
	v_add_f32_e32 v32, v42, v43
	ds_bpermute_b32 v33, v121, v32
	v_cvt_pk_bf16_f32 v37, v40, v41
	global_store_dwordx4 v[48:49], v[34:37], off sc1
	s_nop 1
	s_and_saveexec_b64 s[0:1], s[6:7]
	s_cbranch_execz .LBB0_2679
	s_waitcnt lgkmcnt(0)
	v_add_f32_e32 v34, v32, v33
	s_lshl_b32 s24, s45, 2
	v_lshlrev_b64 v[32:33], 6, v[188:189]
	s_ashr_i32 s25, s24, 31
	v_lshl_add_u64 v[32:33], s[16:17], 0, v[32:33]
	v_lshl_add_u64 v[32:33], s[24:25], 2, v[32:33]
	s_lshl_b32 s4, s40, 2
	v_lshl_add_u64 v[32:33], v[32:33], 0, s[4:5]
	global_store_dword v[32:33], v34, off sc1
.LBB0_2679:
	s_or_b64 exec, exec, s[0:1]
	s_waitcnt vmcnt(14)
	v_lshlrev_b32_e32 v34, 16, v108
	v_and_b32_e32 v35, 0xffff0000, v108
	v_lshlrev_b32_e32 v36, 16, v109
	v_and_b32_e32 v37, 0xffff0000, v109
	v_lshlrev_b32_e32 v38, 16, v110
	v_and_b32_e32 v39, 0xffff0000, v110
	v_lshlrev_b32_e32 v40, 16, v111
	v_and_b32_e32 v41, 0xffff0000, v111
	v_pk_add_f32 v[30:31], v[30:31], v[36:37]
	v_pk_add_f32 v[28:29], v[28:29], v[34:35]
	v_pk_add_f32 v[34:35], v[26:27], v[40:41]
	v_pk_add_f32 v[26:27], v[24:25], v[38:39]
	v_mul_f32_e32 v24, v29, v29
	v_mul_f32_e32 v25, v31, v31
	v_fmac_f32_e32 v24, v28, v28
	v_fmac_f32_e32 v25, v30, v30
	v_add_f32_e32 v24, v24, v25
	v_mul_f32_e32 v25, v27, v27
	v_mul_f32_e32 v36, v35, v35
	v_fmac_f32_e32 v25, v26, v26
	v_fmac_f32_e32 v36, v34, v34
	s_waitcnt vmcnt(14)
	v_lshlrev_b32_e32 v42, 16, v104
	v_and_b32_e32 v43, 0xffff0000, v104
	v_lshlrev_b32_e32 v44, 16, v105
	v_and_b32_e32 v45, 0xffff0000, v105
	v_add_f32_e32 v25, v25, v36
	v_lshlrev_b32_e32 v48, 16, v107
	v_and_b32_e32 v49, 0xffff0000, v107
	v_add_f32_e32 v36, v24, v25
	v_cvt_pk_bf16_f32 v24, v28, v29
	v_cvt_pk_bf16_f32 v25, v30, v31
	v_pk_add_f32 v[22:23], v[22:23], v[44:45]
	v_pk_add_f32 v[20:21], v[20:21], v[42:43]
	v_lshlrev_b32_e32 v46, 16, v106
	v_and_b32_e32 v47, 0xffff0000, v106
	v_cvt_pk_bf16_f32 v26, v26, v27
	v_cvt_pk_bf16_f32 v27, v34, v35
	global_store_dwordx4 v[118:119], v[24:27], off sc1
	s_nop 1
	v_pk_add_f32 v[24:25], v[18:19], v[48:49]
	v_mul_f32_e32 v18, v21, v21
	v_mul_f32_e32 v19, v23, v23
	v_pk_add_f32 v[16:17], v[16:17], v[46:47]
	v_fmac_f32_e32 v18, v20, v20
	v_fmac_f32_e32 v19, v22, v22
	v_add_f32_e32 v18, v18, v19
	v_mul_f32_e32 v19, v17, v17
	v_mul_f32_e32 v26, v25, v25
	v_fmac_f32_e32 v19, v16, v16
	v_fmac_f32_e32 v26, v24, v24
	v_add_f32_e32 v19, v19, v26
	v_add_f32_e32 v18, v18, v19
	v_add_f32_e32 v26, v36, v18
	ds_bpermute_b32 v27, v120, v26
	v_cvt_pk_bf16_f32 v18, v20, v21
	v_cvt_pk_bf16_f32 v20, v16, v17
	s_waitcnt lgkmcnt(1)
	v_lshl_add_u64 v[32:33], v[118:119], 0, s[14:15]
	v_cvt_pk_bf16_f32 v19, v22, v23
	s_waitcnt lgkmcnt(0)
	v_add_f32_e32 v16, v26, v27
	ds_bpermute_b32 v17, v121, v16
	v_cvt_pk_bf16_f32 v21, v24, v25
	global_store_dwordx4 v[32:33], v[18:21], off sc1
	s_nop 1
	s_and_saveexec_b64 s[0:1], s[6:7]
	s_cbranch_execz .LBB0_2681
	s_waitcnt lgkmcnt(0)
	v_add_f32_e32 v18, v16, v17
	s_lshl_b32 s24, s45, 2
	v_lshlrev_b64 v[16:17], 6, v[116:117]
	s_ashr_i32 s25, s24, 31
	v_lshl_add_u64 v[16:17], s[16:17], 0, v[16:17]
	v_lshl_add_u64 v[16:17], s[24:25], 2, v[16:17]
	s_lshl_b32 s4, s40, 2
	v_lshl_add_u64 v[16:17], v[16:17], 0, s[4:5]
	global_store_dword v[16:17], v18, off sc1
.LBB0_2681:
	s_or_b64 exec, exec, s[0:1]
	s_waitcnt vmcnt(15)
	v_lshlrev_b32_e32 v18, 16, v100
	v_and_b32_e32 v19, 0xffff0000, v100
	v_lshlrev_b32_e32 v20, 16, v101
	v_and_b32_e32 v21, 0xffff0000, v101
	v_lshlrev_b32_e32 v22, 16, v102
	v_and_b32_e32 v23, 0xffff0000, v102
	v_lshlrev_b32_e32 v24, 16, v103
	v_and_b32_e32 v25, 0xffff0000, v103
	v_pk_add_f32 v[14:15], v[14:15], v[20:21]
	v_pk_add_f32 v[12:13], v[12:13], v[18:19]
	v_pk_add_f32 v[18:19], v[10:11], v[24:25]
	v_pk_add_f32 v[10:11], v[8:9], v[22:23]
	v_mul_f32_e32 v8, v13, v13
	v_mul_f32_e32 v9, v15, v15
	v_fmac_f32_e32 v8, v12, v12
	v_fmac_f32_e32 v9, v14, v14
	v_add_f32_e32 v8, v8, v9
	v_mul_f32_e32 v9, v11, v11
	v_mul_f32_e32 v20, v19, v19
	v_fmac_f32_e32 v9, v10, v10
	v_fmac_f32_e32 v20, v18, v18
	s_waitcnt vmcnt(15)
	v_lshlrev_b32_e32 v26, 16, v96
	v_and_b32_e32 v27, 0xffff0000, v96
	v_lshlrev_b32_e32 v28, 16, v97
	v_and_b32_e32 v29, 0xffff0000, v97
	v_add_f32_e32 v9, v9, v20
	v_lshlrev_b32_e32 v32, 16, v99
	v_and_b32_e32 v33, 0xffff0000, v99
	v_add_f32_e32 v20, v8, v9
	v_cvt_pk_bf16_f32 v8, v12, v13
	v_cvt_pk_bf16_f32 v9, v14, v15
	v_pk_add_f32 v[6:7], v[6:7], v[28:29]
	v_pk_add_f32 v[4:5], v[4:5], v[26:27]
	v_lshlrev_b32_e32 v30, 16, v98
	v_and_b32_e32 v31, 0xffff0000, v98
	v_cvt_pk_bf16_f32 v10, v10, v11
	v_cvt_pk_bf16_f32 v11, v18, v19
	global_store_dwordx4 v[114:115], v[8:11], off sc1
	s_nop 1
	v_pk_add_f32 v[8:9], v[2:3], v[32:33]
	v_mul_f32_e32 v2, v5, v5
	v_mul_f32_e32 v3, v7, v7
	v_pk_add_f32 v[0:1], v[0:1], v[30:31]
	v_fmac_f32_e32 v2, v4, v4
	v_fmac_f32_e32 v3, v6, v6
	v_add_f32_e32 v2, v2, v3
	v_mul_f32_e32 v3, v1, v1
	v_mul_f32_e32 v10, v9, v9
	v_fmac_f32_e32 v3, v0, v0
	v_fmac_f32_e32 v10, v8, v8
	v_add_f32_e32 v3, v3, v10
	v_add_f32_e32 v2, v2, v3
	v_add_f32_e32 v10, v20, v2
	ds_bpermute_b32 v11, v120, v10
	v_cvt_pk_bf16_f32 v2, v4, v5
	v_cvt_pk_bf16_f32 v4, v0, v1
	s_waitcnt lgkmcnt(1)
	v_lshl_add_u64 v[16:17], v[114:115], 0, s[14:15]
	v_cvt_pk_bf16_f32 v3, v6, v7
	s_waitcnt lgkmcnt(0)
	v_add_f32_e32 v0, v10, v11
	ds_bpermute_b32 v1, v121, v0
	v_cvt_pk_bf16_f32 v5, v8, v9
	global_store_dwordx4 v[16:17], v[2:5], off sc1
	s_nop 1
	s_and_saveexec_b64 s[0:1], s[6:7]
	s_cbranch_execz .LBB0_2683
	s_waitcnt lgkmcnt(0)
	v_add_f32_e32 v2, v0, v1
	s_lshl_b32 s24, s45, 2
	v_lshlrev_b64 v[0:1], 6, v[112:113]
	s_ashr_i32 s25, s24, 31
	v_lshl_add_u64 v[0:1], s[16:17], 0, v[0:1]
	v_lshl_add_u64 v[0:1], s[24:25], 2, v[0:1]
	s_lshl_b32 s4, s40, 2
	v_lshl_add_u64 v[0:1], v[0:1], 0, s[4:5]
	global_store_dword v[0:1], v2, off sc1

.LBB0_2877:
	v_lshl_add_u32 v200, s24, 8, v169
	v_lshl_or_b32 v128, s45, 8, v211
	v_ashrrev_i32_e32 v201, 31, v200
	v_lshlrev_b64 v[130:131], 11, v[200:201]
	v_ashrrev_i32_e32 v129, 31, v128
	v_lshl_add_u64 v[130:131], s[12:13], 0, v[130:131]
	v_lshlrev_b64 v[202:203], 1, v[128:129]
	v_lshl_add_u64 v[224:225], v[130:131], 0, v[202:203]
	global_load_dwordx4 v[216:219], v[224:225], off
	global_load_dwordx4 v[220:223], v[224:225], off offset:256
	v_or_b32_e32 v206, 16, v200
	v_or_b32_e32 v198, 32, v200
	v_or_b32_e32 v194, 48, v200
	v_add_u32_e32 v190, 0x80, v200
	v_add_u32_e32 v186, 0x90, v200
	v_ashrrev_i32_e32 v207, 31, v206
	v_ashrrev_i32_e32 v199, 31, v198
	v_ashrrev_i32_e32 v195, 31, v194
	v_ashrrev_i32_e32 v191, 31, v190
	v_ashrrev_i32_e32 v187, 31, v186
	v_lshlrev_b64 v[128:129], 11, v[206:207]
	v_lshlrev_b64 v[130:131], 11, v[198:199]
	v_lshlrev_b64 v[132:133], 11, v[194:195]
	v_lshlrev_b64 v[134:135], 11, v[190:191]
	v_lshlrev_b64 v[136:137], 11, v[186:187]
	v_lshl_add_u64 v[128:129], s[12:13], 0, v[128:129]
	v_lshl_add_u64 v[130:131], s[12:13], 0, v[130:131]
	v_lshl_add_u64 v[132:133], s[12:13], 0, v[132:133]
	v_lshl_add_u64 v[134:135], s[12:13], 0, v[134:135]
	v_lshl_add_u64 v[136:137], s[12:13], 0, v[136:137]
	v_lshl_add_u64 v[208:209], v[128:129], 0, v[202:203]
	v_lshl_add_u64 v[204:205], v[130:131], 0, v[202:203]
	v_lshl_add_u64 v[196:197], v[132:133], 0, v[202:203]
	v_lshl_add_u64 v[192:193], v[134:135], 0, v[202:203]
	v_lshl_add_u64 v[188:189], v[136:137], 0, v[202:203]
	global_load_dwordx4 v[164:167], v[208:209], off
	global_load_dwordx4 v[160:163], v[208:209], off offset:256
	global_load_dwordx4 v[156:159], v[204:205], off
	global_load_dwordx4 v[152:155], v[204:205], off offset:256
	global_load_dwordx4 v[148:151], v[196:197], off
	global_load_dwordx4 v[144:147], v[196:197], off offset:256
	global_load_dwordx4 v[140:143], v[192:193], off
	global_load_dwordx4 v[136:139], v[192:193], off offset:256
	global_load_dwordx4 v[132:135], v[188:189], off
	global_load_dwordx4 v[128:131], v[188:189], off offset:256
	v_lshl_add_u64 v[226:227], v[224:225], 0, s[14:15]
	s_waitcnt vmcnt(8)
	v_lshlrev_b32_e32 v228, 16, v216
	v_and_b32_e32 v229, 0xffff0000, v216
	v_lshlrev_b32_e32 v216, 16, v217
	v_and_b32_e32 v217, 0xffff0000, v217
	v_lshlrev_b32_e32 v230, 16, v218
	v_and_b32_e32 v231, 0xffff0000, v218
	v_lshlrev_b32_e32 v218, 16, v219
	v_and_b32_e32 v219, 0xffff0000, v219
	v_lshlrev_b32_e32 v232, 16, v220
	v_and_b32_e32 v233, 0xffff0000, v220
	v_lshlrev_b32_e32 v220, 16, v221
	v_and_b32_e32 v221, 0xffff0000, v221
	v_lshlrev_b32_e32 v234, 16, v222
	v_and_b32_e32 v235, 0xffff0000, v222
	v_lshlrev_b32_e32 v222, 16, v223
	v_and_b32_e32 v223, 0xffff0000, v223
	v_pk_add_f32 v[126:127], v[126:127], v[216:217]
	v_pk_add_f32 v[124:125], v[124:125], v[228:229]
	v_pk_add_f32 v[122:123], v[122:123], v[218:219]
	v_pk_add_f32 v[120:121], v[120:121], v[230:231]
	v_pk_add_f32 v[118:119], v[118:119], v[220:221]
	v_pk_add_f32 v[216:217], v[114:115], v[222:223]
	v_mul_f32_e32 v220, v125, v125
	v_mul_f32_e32 v221, v127, v127
	v_mul_f32_e32 v222, v121, v121
	v_mul_f32_e32 v223, v123, v123
	v_pk_add_f32 v[218:219], v[112:113], v[234:235]
	v_cvt_pk_bf16_f32 v112, v124, v125
	v_cvt_pk_bf16_f32 v113, v126, v127
	v_fmac_f32_e32 v220, v124, v124
	v_fmac_f32_e32 v221, v126, v126
	v_fmac_f32_e32 v222, v120, v120
	v_fmac_f32_e32 v223, v122, v122
	v_pk_add_f32 v[116:117], v[116:117], v[232:233]
	v_cvt_pk_bf16_f32 v114, v120, v121
	v_cvt_pk_bf16_f32 v115, v122, v123
	global_store_dwordx4 v[224:225], v[112:115], off sc1
	s_nop 1
	v_add_f32_e32 v112, v220, v221
	v_add_f32_e32 v113, v222, v223
	v_mul_f32_e32 v121, v117, v117
	v_mul_f32_e32 v123, v119, v119
	v_add_f32_e32 v112, v112, v113
	v_mul_f32_e32 v113, v219, v219
	v_mul_f32_e32 v115, v217, v217
	v_fmac_f32_e32 v121, v116, v116
	v_fmac_f32_e32 v123, v118, v118
	v_fmac_f32_e32 v113, v218, v218
	v_fmac_f32_e32 v115, v216, v216
	v_add_f32_e32 v114, v121, v123
	v_add_f32_e32 v113, v113, v115
	v_add_f32_e32 v113, v114, v113
	v_and_b32_e32 v114, 64, v215
	v_add_f32_e32 v112, v112, v113
	v_xor_b32_e32 v113, 16, v215
	v_add_u32_e32 v121, 64, v114
	v_cmp_lt_i32_e32 vcc, v113, v121
	v_cvt_pk_bf16_f32 v114, v116, v117
	v_cvt_pk_bf16_f32 v115, v118, v119
	v_cndmask_b32_e32 v113, v215, v113, vcc
	v_lshlrev_b32_e32 v120, 2, v113
	ds_bpermute_b32 v113, v120, v112
	v_cvt_pk_bf16_f32 v116, v218, v219
	v_cvt_pk_bf16_f32 v117, v216, v217
	global_store_dwordx4 v[226:227], v[114:117], off sc1
	s_nop 1
	s_waitcnt lgkmcnt(0)
	v_add_f32_e32 v112, v112, v113
	v_xor_b32_e32 v113, 32, v215
	v_cmp_lt_i32_e32 vcc, v113, v121
	s_nop 1
	v_cndmask_b32_e32 v113, v215, v113, vcc
	v_lshlrev_b32_e32 v121, 2, v113
	ds_bpermute_b32 v113, v121, v112
	s_and_saveexec_b64 s[0:1], s[6:7]
	s_cbranch_execz .LBB0_2879
	s_waitcnt lgkmcnt(0)
	v_add_f32_e32 v114, v112, v113
	s_lshl_b32 s24, s45, 2
	v_lshlrev_b64 v[112:113], 6, v[200:201]
	s_ashr_i32 s25, s24, 31
	v_lshl_add_u64 v[112:113], s[16:17], 0, v[112:113]
	v_lshl_add_u64 v[112:113], s[24:25], 2, v[112:113]
	s_lshl_b32 s4, s40, 2
	v_lshl_add_u64 v[112:113], v[112:113], 0, s[4:5]
	global_store_dword v[112:113], v114, off sc1
.LBB0_2879:
	s_or_b64 exec, exec, s[0:1]
	v_lshlrev_b32_e32 v114, 16, v164
	v_and_b32_e32 v115, 0xffff0000, v164
	v_lshlrev_b32_e32 v116, 16, v165
	v_and_b32_e32 v117, 0xffff0000, v165
	v_lshlrev_b32_e32 v118, 16, v166
	v_and_b32_e32 v119, 0xffff0000, v166
	v_lshlrev_b32_e32 v122, 16, v167
	v_and_b32_e32 v123, 0xffff0000, v167
	v_pk_add_f32 v[110:111], v[110:111], v[116:117]
	v_pk_add_f32 v[108:109], v[108:109], v[114:115]
	v_pk_add_f32 v[114:115], v[106:107], v[122:123]
	v_pk_add_f32 v[106:107], v[104:105], v[118:119]
	v_mul_f32_e32 v104, v109, v109
	v_mul_f32_e32 v105, v111, v111
	v_fmac_f32_e32 v104, v108, v108
	v_fmac_f32_e32 v105, v110, v110
	v_add_f32_e32 v104, v104, v105
	v_mul_f32_e32 v105, v107, v107
	v_mul_f32_e32 v116, v115, v115
	v_fmac_f32_e32 v105, v106, v106
	v_fmac_f32_e32 v116, v114, v114
	v_lshlrev_b32_e32 v124, 16, v160
	v_and_b32_e32 v125, 0xffff0000, v160
	v_lshlrev_b32_e32 v126, 16, v161
	v_and_b32_e32 v127, 0xffff0000, v161
	v_add_f32_e32 v105, v105, v116
	v_lshlrev_b32_e32 v160, 16, v162
	v_and_b32_e32 v161, 0xffff0000, v162
	v_lshlrev_b32_e32 v162, 16, v163
	v_and_b32_e32 v163, 0xffff0000, v163
	v_add_f32_e32 v116, v104, v105
	v_cvt_pk_bf16_f32 v104, v108, v109
	v_cvt_pk_bf16_f32 v105, v110, v111
	v_pk_add_f32 v[102:103], v[102:103], v[126:127]
	v_pk_add_f32 v[100:101], v[100:101], v[124:125]
	v_cvt_pk_bf16_f32 v106, v106, v107
	v_cvt_pk_bf16_f32 v107, v114, v115
	global_store_dwordx4 v[208:209], v[104:107], off sc1
	s_nop 1
	v_pk_add_f32 v[104:105], v[98:99], v[162:163]
	v_mul_f32_e32 v98, v101, v101
	v_mul_f32_e32 v99, v103, v103
	v_pk_add_f32 v[96:97], v[96:97], v[160:161]
	v_fmac_f32_e32 v98, v100, v100
	v_fmac_f32_e32 v99, v102, v102
	v_add_f32_e32 v98, v98, v99
	v_mul_f32_e32 v99, v97, v97
	v_mul_f32_e32 v106, v105, v105
	v_fmac_f32_e32 v99, v96, v96
	v_fmac_f32_e32 v106, v104, v104
	v_add_f32_e32 v99, v99, v106
	v_add_f32_e32 v98, v98, v99
	v_add_f32_e32 v106, v116, v98
	ds_bpermute_b32 v107, v120, v106
	v_cvt_pk_bf16_f32 v98, v100, v101
	v_cvt_pk_bf16_f32 v100, v96, v97
	s_waitcnt lgkmcnt(1)
	v_lshl_add_u64 v[112:113], v[208:209], 0, s[14:15]
	v_cvt_pk_bf16_f32 v99, v102, v103
	s_waitcnt lgkmcnt(0)
	v_add_f32_e32 v96, v106, v107
	ds_bpermute_b32 v97, v121, v96
	v_cvt_pk_bf16_f32 v101, v104, v105
	global_store_dwordx4 v[112:113], v[98:101], off sc1
	s_nop 1
	s_and_saveexec_b64 s[0:1], s[6:7]
	s_cbranch_execz .LBB0_2881
	s_waitcnt lgkmcnt(0)
	v_add_f32_e32 v98, v96, v97
	s_lshl_b32 s24, s45, 2
	v_lshlrev_b64 v[96:97], 6, v[206:207]
	s_ashr_i32 s25, s24, 31
	v_lshl_add_u64 v[96:97], s[16:17], 0, v[96:97]
	v_lshl_add_u64 v[96:97], s[24:25], 2, v[96:97]
	s_lshl_b32 s4, s40, 2
	v_lshl_add_u64 v[96:97], v[96:97], 0, s[4:5]
	global_store_dword v[96:97], v98, off sc1
.LBB0_2881:
	s_or_b64 exec, exec, s[0:1]
	v_add_u32_e32 v116, 0xa0, v200
	v_ashrrev_i32_e32 v117, 31, v116
	s_waitcnt lgkmcnt(0)
	v_lshlrev_b64 v[96:97], 11, v[116:117]
	v_add_u32_e32 v112, 0xb0, v200
	v_lshl_add_u64 v[96:97], s[12:13], 0, v[96:97]
	v_ashrrev_i32_e32 v113, 31, v112
	v_lshl_add_u64 v[118:119], v[96:97], 0, v[202:203]
	v_lshlrev_b64 v[96:97], 11, v[112:113]
	v_lshl_add_u64 v[96:97], s[12:13], 0, v[96:97]
	v_lshl_add_u64 v[114:115], v[96:97], 0, v[202:203]
	global_load_dwordx4 v[108:111], v[118:119], off
	global_load_dwordx4 v[104:107], v[118:119], off offset:256
	global_load_dwordx4 v[100:103], v[114:115], off
	global_load_dwordx4 v[96:99], v[114:115], off offset:256
	s_waitcnt vmcnt(14)
	v_lshlrev_b32_e32 v124, 16, v156
	v_and_b32_e32 v125, 0xffff0000, v156
	v_lshlrev_b32_e32 v126, 16, v157
	v_and_b32_e32 v127, 0xffff0000, v157
	v_lshlrev_b32_e32 v156, 16, v158
	v_and_b32_e32 v157, 0xffff0000, v158
	v_lshlrev_b32_e32 v158, 16, v159
	v_and_b32_e32 v159, 0xffff0000, v159
	v_pk_add_f32 v[94:95], v[94:95], v[126:127]
	v_pk_add_f32 v[92:93], v[92:93], v[124:125]
	v_pk_add_f32 v[124:125], v[90:91], v[158:159]
	v_pk_add_f32 v[90:91], v[88:89], v[156:157]
	v_mul_f32_e32 v88, v93, v93
	v_mul_f32_e32 v89, v95, v95
	v_fmac_f32_e32 v88, v92, v92
	v_fmac_f32_e32 v89, v94, v94
	v_add_f32_e32 v88, v88, v89
	v_mul_f32_e32 v89, v91, v91
	v_mul_f32_e32 v126, v125, v125
	v_fmac_f32_e32 v89, v90, v90
	v_fmac_f32_e32 v126, v124, v124
	v_lshlrev_b32_e32 v160, 16, v152
	v_and_b32_e32 v161, 0xffff0000, v152
	v_lshlrev_b32_e32 v152, 16, v153
	v_and_b32_e32 v153, 0xffff0000, v153
	v_add_f32_e32 v89, v89, v126
	v_lshlrev_b32_e32 v162, 16, v154
	v_and_b32_e32 v163, 0xffff0000, v154
	v_lshlrev_b32_e32 v154, 16, v155
	v_and_b32_e32 v155, 0xffff0000, v155
	v_add_f32_e32 v126, v88, v89
	v_cvt_pk_bf16_f32 v88, v92, v93
	v_cvt_pk_bf16_f32 v89, v94, v95
	v_pk_add_f32 v[86:87], v[86:87], v[152:153]
	v_pk_add_f32 v[84:85], v[84:85], v[160:161]
	v_cvt_pk_bf16_f32 v90, v90, v91
	v_cvt_pk_bf16_f32 v91, v124, v125
	global_store_dwordx4 v[204:205], v[88:91], off sc1
	s_nop 1
	v_pk_add_f32 v[88:89], v[82:83], v[154:155]
	v_mul_f32_e32 v82, v85, v85
	v_mul_f32_e32 v83, v87, v87
	v_pk_add_f32 v[80:81], v[80:81], v[162:163]
	v_fmac_f32_e32 v82, v84, v84
	v_fmac_f32_e32 v83, v86, v86
	v_add_f32_e32 v82, v82, v83
	v_mul_f32_e32 v83, v81, v81
	v_mul_f32_e32 v90, v89, v89
	v_fmac_f32_e32 v83, v80, v80
	v_fmac_f32_e32 v90, v88, v88
	v_add_f32_e32 v83, v83, v90
	v_add_f32_e32 v82, v82, v83
	v_add_f32_e32 v90, v126, v82
	ds_bpermute_b32 v91, v120, v90
	v_cvt_pk_bf16_f32 v82, v84, v85
	v_cvt_pk_bf16_f32 v84, v80, v81
	v_lshl_add_u64 v[122:123], v[204:205], 0, s[14:15]
	v_cvt_pk_bf16_f32 v83, v86, v87
	s_waitcnt lgkmcnt(0)
	v_add_f32_e32 v80, v90, v91
	ds_bpermute_b32 v81, v121, v80
	v_cvt_pk_bf16_f32 v85, v88, v89
	global_store_dwordx4 v[122:123], v[82:85], off sc1
	s_nop 1
	s_and_saveexec_b64 s[0:1], s[6:7]
	s_cbranch_execz .LBB0_2883
	s_waitcnt lgkmcnt(0)
	v_add_f32_e32 v82, v80, v81
	s_lshl_b32 s24, s45, 2
	v_lshlrev_b64 v[80:81], 6, v[198:199]
	s_ashr_i32 s25, s24, 31
	v_lshl_add_u64 v[80:81], s[16:17], 0, v[80:81]
	v_lshl_add_u64 v[80:81], s[24:25], 2, v[80:81]
	s_lshl_b32 s4, s40, 2
	v_lshl_add_u64 v[80:81], v[80:81], 0, s[4:5]
	global_store_dword v[80:81], v82, off sc1
.LBB0_2883:
	s_or_b64 exec, exec, s[0:1]
	v_lshlrev_b32_e32 v82, 16, v148
	v_and_b32_e32 v83, 0xffff0000, v148
	v_lshlrev_b32_e32 v84, 16, v149
	v_and_b32_e32 v85, 0xffff0000, v149
	v_lshlrev_b32_e32 v86, 16, v150
	v_and_b32_e32 v87, 0xffff0000, v150
	v_lshlrev_b32_e32 v88, 16, v151
	v_and_b32_e32 v89, 0xffff0000, v151
	v_pk_add_f32 v[78:79], v[78:79], v[84:85]
	v_pk_add_f32 v[76:77], v[76:77], v[82:83]
	v_pk_add_f32 v[82:83], v[74:75], v[88:89]
	v_pk_add_f32 v[74:75], v[72:73], v[86:87]
	v_mul_f32_e32 v72, v77, v77
	v_mul_f32_e32 v73, v79, v79
	v_fmac_f32_e32 v72, v76, v76
	v_fmac_f32_e32 v73, v78, v78
	v_add_f32_e32 v72, v72, v73
	v_mul_f32_e32 v73, v75, v75
	v_mul_f32_e32 v84, v83, v83
	v_fmac_f32_e32 v73, v74, v74
	v_fmac_f32_e32 v84, v82, v82
	v_lshlrev_b32_e32 v90, 16, v144
	v_and_b32_e32 v91, 0xffff0000, v144
	v_lshlrev_b32_e32 v92, 16, v145
	v_and_b32_e32 v93, 0xffff0000, v145
	v_add_f32_e32 v73, v73, v84
	v_lshlrev_b32_e32 v122, 16, v147
	v_and_b32_e32 v123, 0xffff0000, v147
	v_add_f32_e32 v84, v72, v73
	v_cvt_pk_bf16_f32 v72, v76, v77
	v_cvt_pk_bf16_f32 v73, v78, v79
	v_pk_add_f32 v[70:71], v[70:71], v[92:93]
	v_pk_add_f32 v[68:69], v[68:69], v[90:91]
	v_lshlrev_b32_e32 v94, 16, v146
	v_and_b32_e32 v95, 0xffff0000, v146
	v_cvt_pk_bf16_f32 v74, v74, v75
	v_cvt_pk_bf16_f32 v75, v82, v83
	global_store_dwordx4 v[196:197], v[72:75], off sc1
	s_nop 1
	v_pk_add_f32 v[72:73], v[66:67], v[122:123]
	v_mul_f32_e32 v66, v69, v69
	v_mul_f32_e32 v67, v71, v71
	v_pk_add_f32 v[64:65], v[64:65], v[94:95]
	v_fmac_f32_e32 v66, v68, v68
	v_fmac_f32_e32 v67, v70, v70
	v_add_f32_e32 v66, v66, v67
	v_mul_f32_e32 v67, v65, v65
	v_mul_f32_e32 v74, v73, v73
	v_fmac_f32_e32 v67, v64, v64
	v_fmac_f32_e32 v74, v72, v72
	v_add_f32_e32 v67, v67, v74
	v_add_f32_e32 v66, v66, v67
	v_add_f32_e32 v74, v84, v66
	ds_bpermute_b32 v75, v120, v74
	v_cvt_pk_bf16_f32 v66, v68, v69
	v_cvt_pk_bf16_f32 v68, v64, v65
	s_waitcnt lgkmcnt(1)
	v_lshl_add_u64 v[80:81], v[196:197], 0, s[14:15]
	v_cvt_pk_bf16_f32 v67, v70, v71
	s_waitcnt lgkmcnt(0)
	v_add_f32_e32 v64, v74, v75
	ds_bpermute_b32 v65, v121, v64
	v_cvt_pk_bf16_f32 v69, v72, v73
	global_store_dwordx4 v[80:81], v[66:69], off sc1
	s_nop 1
	s_and_saveexec_b64 s[0:1], s[6:7]
	s_cbranch_execz .LBB0_2885
	s_waitcnt lgkmcnt(0)
	v_add_f32_e32 v66, v64, v65
	s_lshl_b32 s24, s45, 2
	v_lshlrev_b64 v[64:65], 6, v[194:195]
	s_ashr_i32 s25, s24, 31
	v_lshl_add_u64 v[64:65], s[16:17], 0, v[64:65]
	v_lshl_add_u64 v[64:65], s[24:25], 2, v[64:65]
	s_lshl_b32 s4, s40, 2
	v_lshl_add_u64 v[64:65], v[64:65], 0, s[4:5]
	global_store_dword v[64:65], v66, off sc1
.LBB0_2885:
	s_or_b64 exec, exec, s[0:1]
	s_waitcnt vmcnt(16)
	v_lshlrev_b32_e32 v66, 16, v140
	v_and_b32_e32 v67, 0xffff0000, v140
	v_lshlrev_b32_e32 v68, 16, v141
	v_and_b32_e32 v69, 0xffff0000, v141
	v_lshlrev_b32_e32 v70, 16, v142
	v_and_b32_e32 v71, 0xffff0000, v142
	v_lshlrev_b32_e32 v72, 16, v143
	v_and_b32_e32 v73, 0xffff0000, v143
	v_pk_add_f32 v[62:63], v[62:63], v[68:69]
	v_pk_add_f32 v[60:61], v[60:61], v[66:67]
	v_pk_add_f32 v[66:67], v[58:59], v[72:73]
	v_pk_add_f32 v[58:59], v[56:57], v[70:71]
	v_mul_f32_e32 v56, v61, v61
	v_mul_f32_e32 v57, v63, v63
	v_fmac_f32_e32 v56, v60, v60
	v_fmac_f32_e32 v57, v62, v62
	v_add_f32_e32 v56, v56, v57
	v_mul_f32_e32 v57, v59, v59
	v_mul_f32_e32 v68, v67, v67
	v_fmac_f32_e32 v57, v58, v58
	v_fmac_f32_e32 v68, v66, v66
	v_lshlrev_b32_e32 v74, 16, v136
	v_and_b32_e32 v75, 0xffff0000, v136
	v_lshlrev_b32_e32 v76, 16, v137
	v_and_b32_e32 v77, 0xffff0000, v137
	v_add_f32_e32 v57, v57, v68
	v_lshlrev_b32_e32 v80, 16, v139
	v_and_b32_e32 v81, 0xffff0000, v139
	v_add_f32_e32 v68, v56, v57
	v_cvt_pk_bf16_f32 v56, v60, v61
	v_cvt_pk_bf16_f32 v57, v62, v63
	v_pk_add_f32 v[54:55], v[54:55], v[76:77]
	v_pk_add_f32 v[52:53], v[52:53], v[74:75]
	v_lshlrev_b32_e32 v78, 16, v138
	v_and_b32_e32 v79, 0xffff0000, v138
	v_cvt_pk_bf16_f32 v58, v58, v59
	v_cvt_pk_bf16_f32 v59, v66, v67
	global_store_dwordx4 v[192:193], v[56:59], off sc1
	s_nop 1
	v_pk_add_f32 v[56:57], v[50:51], v[80:81]
	v_mul_f32_e32 v50, v53, v53
	v_mul_f32_e32 v51, v55, v55
	v_pk_add_f32 v[48:49], v[48:49], v[78:79]
	v_fmac_f32_e32 v50, v52, v52
	v_fmac_f32_e32 v51, v54, v54
	v_add_f32_e32 v50, v50, v51
	v_mul_f32_e32 v51, v49, v49
	v_mul_f32_e32 v58, v57, v57
	v_fmac_f32_e32 v51, v48, v48
	v_fmac_f32_e32 v58, v56, v56
	v_add_f32_e32 v51, v51, v58
	v_add_f32_e32 v50, v50, v51
	v_add_f32_e32 v58, v68, v50
	ds_bpermute_b32 v59, v120, v58
	v_cvt_pk_bf16_f32 v50, v52, v53
	v_cvt_pk_bf16_f32 v52, v48, v49
	s_waitcnt lgkmcnt(1)
	v_lshl_add_u64 v[64:65], v[192:193], 0, s[14:15]
	v_cvt_pk_bf16_f32 v51, v54, v55
	s_waitcnt lgkmcnt(0)
	v_add_f32_e32 v48, v58, v59
	ds_bpermute_b32 v49, v121, v48
	v_cvt_pk_bf16_f32 v53, v56, v57
	global_store_dwordx4 v[64:65], v[50:53], off sc1
	s_nop 1
	s_and_saveexec_b64 s[0:1], s[6:7]
	s_cbranch_execz .LBB0_2887
	s_waitcnt lgkmcnt(0)
	v_add_f32_e32 v50, v48, v49
	s_lshl_b32 s24, s45, 2
	v_lshlrev_b64 v[48:49], 6, v[190:191]
	s_ashr_i32 s25, s24, 31
	v_lshl_add_u64 v[48:49], s[16:17], 0, v[48:49]
	v_lshl_add_u64 v[48:49], s[24:25], 2, v[48:49]
	s_lshl_b32 s4, s40, 2
	v_lshl_add_u64 v[48:49], v[48:49], 0, s[4:5]
	global_store_dword v[48:49], v50, off sc1
.LBB0_2887:
	s_or_b64 exec, exec, s[0:1]
	v_lshlrev_b32_e32 v50, 16, v132
	v_and_b32_e32 v51, 0xffff0000, v132
	v_lshlrev_b32_e32 v52, 16, v133
	v_and_b32_e32 v53, 0xffff0000, v133
	v_lshlrev_b32_e32 v54, 16, v134
	v_and_b32_e32 v55, 0xffff0000, v134
	v_lshlrev_b32_e32 v56, 16, v135
	v_and_b32_e32 v57, 0xffff0000, v135
	v_pk_add_f32 v[46:47], v[46:47], v[52:53]
	v_pk_add_f32 v[44:45], v[44:45], v[50:51]
	v_pk_add_f32 v[50:51], v[42:43], v[56:57]
	v_pk_add_f32 v[42:43], v[40:41], v[54:55]
	v_mul_f32_e32 v40, v45, v45
	v_mul_f32_e32 v41, v47, v47
	v_fmac_f32_e32 v40, v44, v44
	v_fmac_f32_e32 v41, v46, v46
	v_add_f32_e32 v40, v40, v41
	v_mul_f32_e32 v41, v43, v43
	v_mul_f32_e32 v52, v51, v51
	v_fmac_f32_e32 v41, v42, v42
	v_fmac_f32_e32 v52, v50, v50
	v_lshlrev_b32_e32 v58, 16, v128
	v_and_b32_e32 v59, 0xffff0000, v128
	v_lshlrev_b32_e32 v60, 16, v129
	v_and_b32_e32 v61, 0xffff0000, v129
	v_add_f32_e32 v41, v41, v52
	v_lshlrev_b32_e32 v64, 16, v131
	v_and_b32_e32 v65, 0xffff0000, v131
	v_add_f32_e32 v52, v40, v41
	v_cvt_pk_bf16_f32 v40, v44, v45
	v_cvt_pk_bf16_f32 v41, v46, v47
	v_pk_add_f32 v[38:39], v[38:39], v[60:61]
	v_pk_add_f32 v[36:37], v[36:37], v[58:59]
	v_lshlrev_b32_e32 v62, 16, v130
	v_and_b32_e32 v63, 0xffff0000, v130
	v_cvt_pk_bf16_f32 v42, v42, v43
	v_cvt_pk_bf16_f32 v43, v50, v51
	global_store_dwordx4 v[188:189], v[40:43], off sc1
	s_nop 1
	v_pk_add_f32 v[40:41], v[34:35], v[64:65]
	v_mul_f32_e32 v34, v37, v37
	v_mul_f32_e32 v35, v39, v39
	v_pk_add_f32 v[32:33], v[32:33], v[62:63]
	v_fmac_f32_e32 v34, v36, v36
	v_fmac_f32_e32 v35, v38, v38
	v_add_f32_e32 v34, v34, v35
	v_mul_f32_e32 v35, v33, v33
	v_mul_f32_e32 v42, v41, v41
	v_fmac_f32_e32 v35, v32, v32
	v_fmac_f32_e32 v42, v40, v40
	v_add_f32_e32 v35, v35, v42
	v_add_f32_e32 v34, v34, v35
	v_add_f32_e32 v42, v52, v34
	ds_bpermute_b32 v43, v120, v42
	v_cvt_pk_bf16_f32 v34, v36, v37
	v_cvt_pk_bf16_f32 v36, v32, v33
	s_waitcnt lgkmcnt(1)
	v_lshl_add_u64 v[48:49], v[188:189], 0, s[14:15]
	v_cvt_pk_bf16_f32 v35, v38, v39
	s_waitcnt lgkmcnt(0)
	v_add_f32_e32 v32, v42, v43
	ds_bpermute_b32 v33, v121, v32
	v_cvt_pk_bf16_f32 v37, v40, v41
	global_store_dwordx4 v[48:49], v[34:37], off sc1
	s_nop 1
	s_and_saveexec_b64 s[0:1], s[6:7]
	s_cbranch_execz .LBB0_2889
	s_waitcnt lgkmcnt(0)
	v_add_f32_e32 v34, v32, v33
	s_lshl_b32 s24, s45, 2
	v_lshlrev_b64 v[32:33], 6, v[186:187]
	s_ashr_i32 s25, s24, 31
	v_lshl_add_u64 v[32:33], s[16:17], 0, v[32:33]
	v_lshl_add_u64 v[32:33], s[24:25], 2, v[32:33]
	s_lshl_b32 s4, s40, 2
	v_lshl_add_u64 v[32:33], v[32:33], 0, s[4:5]
	global_store_dword v[32:33], v34, off sc1

.LBB0_2930:
	s_andn2_saveexec_b64 s[0:1], s[6:7]
	s_cbranch_execz .LBB0_2949
	s_mov_b64 s[0:1], exec
	s_waitcnt lgkmcnt(0)
	s_waitcnt vmcnt(0)
	v_mbcnt_lo_u32_b32 v1, s0, 0
	s_add_u32 s6, s70, 0x3400
	v_mbcnt_hi_u32_b32 v1, s1, v1
	s_addc_u32 s7, s71, 0
	v_cmp_eq_u32_e32 vcc, 0, v1
	s_and_saveexec_b64 s[8:9], vcc
	s_cbranch_execz .LBB0_2933
	s_bcnt1_i32_b64 s0, s[0:1]
	v_mov_b32_e32 v2, 0
	v_mov_b32_e32 v3, s0
	global_atomic_add v2, v2, v3, s[6:7] sc0
